# P1 lean epilogue output rows kept in registers and stored from the next tile prologue after its first 8 LDS-DMA loads
# speedup vs baseline: 1.0300x; 1.0025x over previous
; DEV void phase1(const Params& p, const int base_item) {
;   const int nwg = MKV_IN_P2 ? 2816 : 2816 + 64;
;   const int Lbeg = base_item >= 0 ? base_item : (int)blockIdx.x, Lend = base_item >= 0 ? base_item + 1 : nwg;
; #pragma unroll 1
;   for (int L = Lbeg; L < Lend; L += gridDim.x) {
;     const bf16_t* a; const bf16_t* w; int brow, bcol; bool vt;
;     EpiVT ev; EpiP1 e;
;     e.bmat = (const float*)(p.ws + OFF_B); e.keT = (bf16_t*)(p.ws + OFF_KET); e.ld = 2048; e.scale = 1.f; e.mode = 0; e.out = nullptr; e.segstart = 0;
;     ev.out = nullptr; ev.nch = 2048; ev.tshift = 11; ev.segstart = 0;
;     if (L < 2816) {
.LBB0_1256:
	s_and_b64 vcc, exec, s[0:1]
	s_cbranch_vccz .LBB0_1258
	v_readlane_b32 s0, v254, 6
	v_readlane_b32 s1, v254, 7
	s_andn2_b64 vcc, exec, s[0:1]
	s_mov_b32 s34, s70
	s_mov_b32 s41, 0
	s_cbranch_vccz .LBB0_1556

; #define STAGE(P, BASE, br, kt) do { const char* _gb = (const char*)(BASE) + (((long)(br) * K + (long)(kt) * BK) << 1); \
;     __builtin_amdgcn_global_load_lds((const unsigned*)(_gb + so0), (unsigned*)((char*)(P) + tb), 16, 0, 0); \
;     __builtin_amdgcn_global_load_lds((const unsigned*)(_gb + so1), (unsigned*)((char*)(P) + tb + 8192), 16, 0, 0); } while (0)
; #define WAIT_V(n) asm volatile("s_waitcnt vmcnt(" #n ")" ::: "memory")
; #define BAR __builtin_amdgcn_s_barrier()
; template <bool SWAP, class Epi>
; DEV void gemm_tile(const bf16_t* __restrict__ A, const bf16_t* __restrict__ Bt, const int K, const int brow, const int bcol, const Epi& epi) {
;     ...
;   WAIT_V(0);
;   __syncthreads();
;   STAGE(SB(0, 0), Bt, bcol, 0); STAGE(SA(0, 0), A, brow, 0);
;   STAGE(SB(0, 1), Bt, bcol + HALF, 0); STAGE(SA(0, 1), A, brow + HALF, 0);
;   if (wr == 1) BAR;
;   WAIT_V(4); BAR;
;   STAGE(SB(1, 0), Bt, bcol, 1); STAGE(SA(1, 0), A, brow, 1); STAGE(SB(1, 1), Bt, bcol + HALF, 1);
.LBB0_1573:
	s_sext_i32_i16 s4, s20
	s_bfe_u32 s4, s4, 0x3001c
	s_add_i32 s4, s20, s4
	s_sext_i32_i16 s5, s4
	s_and_b32 s4, s4, 0xfff8
	s_sub_i32 s4, s20, s4
	s_sext_i32_i16 s4, s4
	s_lshl_b32 s13, s13, 11
	s_lshl_b32 s4, s4, 8
	s_lshl_b32 s5, s5, 5
	s_mov_b64 s[18:19], -1
	s_add_i32 s4, s4, s13
	s_andn2_b64 vcc, exec, s[6:7]
	s_and_b32 s6, s5, 0xffffff00
	s_cbranch_vccz .LBB0_2095
	v_mov_b32_e32 v198, v179
	s_ashr_i32 s7, s6, 31
	v_ashrrev_i32_e32 v0, 31, v198
	v_lshrrev_b32_e32 v0, 26, v0
	v_add_u32_e32 v0, v198, v0
	v_ashrrev_i32_e32 v2, 6, v0
	v_bfe_i32 v0, v198, 27, 1
	v_lshlrev_b32_e32 v3, 4, v198
	v_lshrrev_b32_e32 v0, 22, v0
	v_add_u32_e32 v0, v3, v0
	v_and_b32_e32 v0, 0xfffffc00, v0
	v_sub_u32_e32 v0, v3, v0
	v_lshrrev_b32_e32 v1, 4, v0
	v_bitop3_b32 v1, v1, v0, 32 bitop3:0x6c
	v_ashrrev_i32_e32 v0, 31, v0
	v_lshrrev_b32_e32 v0, 26, v0
	v_lshlrev_b32_e32 v4, 3, v2
	v_add_u32_e32 v0, v1, v0
	v_and_b32_e32 v6, 0xffff0, v4
	v_ashrrev_i32_e32 v4, 6, v0
	v_mul_i32_i24_e32 v5, 64, v4
	v_sub_u32_e32 v1, v1, v5
	v_lshlrev_b32_e32 v0, 5, v2
	v_ashrrev_i16_sdwa v1, v218, sext(v1) dst_sel:DWORD dst_unused:UNUSED_PAD src0_sel:DWORD src1_sel:BYTE_0
	v_and_b32_e32 v0, 32, v0
	v_bfe_i32 v5, v1, 0, 16
	v_add_u32_e32 v0, v0, v5
	v_add_lshl_u32 v1, v4, v6, 12
	v_lshl_add_u32 v176, v0, 1, v1
	v_add_u32_e32 v0, 0x2000, v3
	v_ashrrev_i32_e32 v1, 31, v0
	v_lshrrev_b32_e32 v1, 22, v1
	v_add_u32_e32 v1, v0, v1
	v_ashrrev_i32_e32 v6, 10, v1
	v_mul_i32_i24_e32 v1, 0x400, v6
	s_lshl_b64 s[18:19], s[6:7], 12
	v_sub_u32_e32 v0, v0, v1
	s_add_u32 s22, s62, s18
	v_lshrrev_b32_e32 v1, 4, v0
	s_addc_u32 s23, s63, s19
	s_add_i32 s7, 0, 0x10000
	v_bitop3_b32 v0, v1, v0, 32 bitop3:0x6c
	v_add_u32_e32 v141, s7, v3
	v_ashrrev_i32_e32 v7, 31, v0
	v_readfirstlane_b32 s5, v141
	v_add_u32_e32 v142, 0x2000, v141
	v_lshrrev_b32_e32 v7, 26, v7
	s_mov_b32 m0, s5
	v_readfirstlane_b32 s5, v142
	v_add_u32_e32 v8, v0, v7
	s_waitcnt vmcnt(0)
	s_waitcnt lgkmcnt(0)
	s_barrier
	global_load_lds_dwordx4 v176, s[22:23]
	s_mov_b32 m0, s5
	s_ashr_i32 s5, s4, 31
	v_ashrrev_i32_e32 v7, 6, v8
	v_and_b32_e32 v8, 0xc0, v8
	s_lshl_b64 s[20:21], s[4:5], 12
	v_readlane_b32 s30, v253, 52
	v_sub_u32_e32 v0, v0, v8
	v_readlane_b32 s31, v253, 53
	s_add_u32 s24, s30, s20
	v_lshlrev_b32_e32 v1, 3, v6
	v_lshlrev_b32_e32 v9, 5, v6
	v_ashrrev_i16_sdwa v0, v218, sext(v0) dst_sel:DWORD dst_unused:UNUSED_PAD src0_sel:DWORD src1_sel:BYTE_0
	s_addc_u32 s25, s31, s21
	s_or_b32 s26, s6, 0x80
	v_and_b32_e32 v1, 0xffff0, v1
	v_and_b32_e32 v9, 32, v9
	v_bfe_i32 v8, v0, 0, 16
	s_ashr_i32 s27, s26, 31
	v_add_u32_e32 v0, v9, v8
	v_add_lshl_u32 v1, v7, v1, 12
	v_add_u32_e32 v143, 0, v3
	s_lshl_b64 s[26:27], s[26:27], 12
	v_lshl_add_u32 v0, v0, 1, v1
	v_readfirstlane_b32 s5, v143
	v_add_u32_e32 v144, 0x2000, v143
	s_add_u32 s26, s62, s26
	global_load_lds_dwordx4 v0, s[22:23]
	s_mov_b32 m0, s5
	v_readfirstlane_b32 s5, v144
	s_addc_u32 s27, s63, s27
	v_add_u32_e32 v145, s72, v3
	s_or_b32 s28, s4, 0x80
	global_load_lds_dwordx4 v176, s[24:25]
	s_mov_b32 m0, s5
	v_readfirstlane_b32 s5, v145
	v_add_u32_e32 v146, 0x2000, v145
	s_ashr_i32 s29, s28, 31
	global_load_lds_dwordx4 v0, s[24:25]
	s_mov_b32 m0, s5
	v_readfirstlane_b32 s5, v146
	s_lshl_b64 s[28:29], s[28:29], 12
	v_add_u32_e32 v147, 0x4000, v143
	global_load_lds_dwordx4 v176, s[26:27]
	s_mov_b32 m0, s5
	s_add_u32 s28, s30, s28
	v_readfirstlane_b32 s5, v147
	v_add_u32_e32 v148, 0x6000, v143
	global_load_lds_dwordx4 v0, s[26:27]
	s_addc_u32 s29, s31, s29
	s_mov_b32 m0, s5
	v_readfirstlane_b32 s5, v148
	global_load_lds_dwordx4 v176, s[28:29]
	s_mov_b32 m0, s5
	v_ashrrev_i32_e32 v9, 8, v198
	global_load_lds_dwordx4 v0, s[28:29]
	s_cmp_eq_u32 s41, 0
	s_cbranch_scc1 .Lp1d_nost_a
	global_store_dwordx4 v62, v[64:67], s[38:39] nt
	v_add_u32_e32 v62, s40, v62
	global_store_dwordx4 v63, v[68:71], s[38:39] nt
	v_add_u32_e32 v63, s40, v63
	global_store_dwordx4 v62, v[72:75], s[38:39] nt
	v_add_u32_e32 v62, s40, v62
	global_store_dwordx4 v63, v[76:79], s[38:39] nt
	v_add_u32_e32 v63, s40, v63
	global_store_dwordx4 v62, v[80:83], s[38:39] nt
	v_add_u32_e32 v62, s40, v62
	global_store_dwordx4 v63, v[84:87], s[38:39] nt
	v_add_u32_e32 v63, s40, v63
	global_store_dwordx4 v62, v[88:91], s[38:39] nt
	v_add_u32_e32 v62, s40, v62
	global_store_dwordx4 v63, v[92:95], s[38:39] nt
	v_add_u32_e32 v63, s40, v63
	global_store_dwordx4 v62, v[96:99], s[38:39] nt
	v_add_u32_e32 v62, s40, v62
	global_store_dwordx4 v63, v[100:103], s[38:39] nt
	v_add_u32_e32 v63, s40, v63
	global_store_dwordx4 v62, v[104:107], s[38:39] nt
	v_add_u32_e32 v62, s40, v62
	global_store_dwordx4 v63, v[108:111], s[38:39] nt
	v_add_u32_e32 v63, s40, v63
	global_store_dwordx4 v62, v[112:115], s[38:39] nt
	v_add_u32_e32 v62, s40, v62
	global_store_dwordx4 v63, v[116:119], s[38:39] nt
	v_add_u32_e32 v63, s40, v63
	global_store_dwordx4 v62, v[120:123], s[38:39] nt
	global_store_dwordx4 v63, v[124:127], s[38:39] nt
.Lp1d_nost_a:
	v_cmp_eq_u32_e32 vcc, 1, v9
	s_and_saveexec_b64 s[30:31], vcc
	s_cbranch_execz .LBB0_1576
	s_barrier
.LBB0_1576:
	s_or_b64 exec, exec, s[30:31]
	v_mov_b32_e32 v1, v177
	v_lshl_add_u64 v[12:13], s[22:23], 0, v[0:1]
	v_lshl_add_u64 v[16:17], s[24:25], 0, v[0:1]
	v_lshl_add_u64 v[20:21], s[26:27], 0, v[0:1]
	v_lshl_add_u64 v[128:129], s[28:29], 0, v[0:1]
	v_and_b32_e32 v0, 15, v198
	v_lshlrev_b32_e32 v23, 2, v198
	v_and_b32_e32 v1, 48, v198
	v_lshlrev_b32_e32 v0, 6, v0
	v_and_b32_e32 v23, 32, v23
	v_or_b32_e32 v22, v0, v1
	v_bitop3_b32 v0, v0, v23, v1 bitop3:0x36
	v_lshlrev_b32_e32 v1, 13, v9
	v_add_u32_e32 v150, s77, v3
	v_lshl_add_u64 v[10:11], s[22:23], 0, v[176:177]
	v_bitop3_b32 v9, v22, v1, v23 bitop3:0xde
	v_lshlrev_b32_e32 v1, 6, v198
	s_mov_b64 s[22:23], 0x80
	v_readfirstlane_b32 s5, v150
	v_add_u32_e32 v151, 0x2000, v150
	v_and_or_b32 v149, v1, s73, v0
	v_lshl_add_u64 v[0:1], v[10:11], 0, s[22:23]
	s_mov_b32 m0, s5
	v_readfirstlane_b32 s5, v151
	v_add_u32_e32 v152, 0x8000, v143
	v_lshl_add_u64 v[14:15], s[24:25], 0, v[176:177]
	s_cmp_eq_u32 s41, 0
	s_cbranch_scc1 .Lp1d_w4_a
	s_waitcnt vmcnt(20)
	s_branch .Lp1d_w4d_a

; #define STAGE(P, BASE, br, kt) do { const char* _gb = (const char*)(BASE) + (((long)(br) * K + (long)(kt) * BK) << 1); \
;     __builtin_amdgcn_global_load_lds((const unsigned*)(_gb + so0), (unsigned*)((char*)(P) + tb), 16, 0, 0); \
;     __builtin_amdgcn_global_load_lds((const unsigned*)(_gb + so1), (unsigned*)((char*)(P) + tb + 8192), 16, 0, 0); } while (0)
; #define WAIT_V(n) asm volatile("s_waitcnt vmcnt(" #n ")" ::: "memory")
; #define BAR __builtin_amdgcn_s_barrier()
; template <bool SWAP, class Epi>
; DEV void gemm_tile(const bf16_t* __restrict__ A, const bf16_t* __restrict__ Bt, const int K, const int brow, const int bcol, const Epi& epi) {
;     ...
;   f32x4 acc[2][2][4][2] = {};
;   bf16x8 At[4][2], B0[2][2], B1[2][2];
;   const int nt = K / BK;
;   const int tb = tidx * 16;
;   unsigned so0, so1;
;   { int r_, c_; stage_rc(tb, r_, c_); so0 = (unsigned)(r_ * K + c_) * 2u; stage_rc(tb + 8192, r_, c_); so1 = (unsigned)(r_ * K + c_) * 2u; }
;   const int tb16 = (fr * 64 + fq * 16) ^ ((fr >> 3) << 5);
;   const int a_rd = wr * 8192 + tb16, b_rd = wc * 4096 + tb16;
;   WAIT_V(0);
;   __syncthreads();
;   STAGE(SB(0, 0), Bt, bcol, 0); STAGE(SA(0, 0), A, brow, 0);
;   STAGE(SB(0, 1), Bt, bcol + HALF, 0); STAGE(SA(0, 1), A, brow + HALF, 0);
;   if (wr == 1) BAR;
;   WAIT_V(4); BAR;
;   STAGE(SB(1, 0), Bt, bcol, 1); STAGE(SA(1, 0), A, brow, 1); STAGE(SB(1, 1), Bt, bcol + HALF, 1);
;   WAIT_V(6); BAR;
.Lp1d_w4d_a:
	s_barrier
	global_load_lds_dwordx4 v[0:1], off
	v_lshl_add_u64 v[0:1], v[12:13], 0, s[22:23]
	s_mov_b32 m0, s5
	v_readfirstlane_b32 s5, v152
	v_add_u32_e32 v153, 0xa000, v143
	global_load_lds_dwordx4 v[0:1], off
	v_lshl_add_u64 v[0:1], v[14:15], 0, s[22:23]
	s_mov_b32 m0, s5
	v_readfirstlane_b32 s5, v153
	v_add_u32_e32 v154, s78, v3
	v_lshl_add_u64 v[18:19], s[26:27], 0, v[176:177]
	global_load_lds_dwordx4 v[0:1], off
	v_lshl_add_u64 v[0:1], v[16:17], 0, s[22:23]
	s_mov_b32 m0, s5
	v_readfirstlane_b32 s5, v154
	v_add_u32_e32 v155, 0x2000, v154
	global_load_lds_dwordx4 v[0:1], off
	v_lshl_add_u64 v[0:1], v[18:19], 0, s[22:23]
	s_mov_b32 m0, s5
	v_readfirstlane_b32 s5, v155
	global_load_lds_dwordx4 v[0:1], off
	v_lshl_add_u64 v[0:1], v[20:21], 0, s[22:23]
	s_mov_b32 m0, s5
	v_lshl_add_u64 v[130:131], s[28:29], 0, v[176:177]
	global_load_lds_dwordx4 v[0:1], off
	v_lshlrev_b32_e32 v0, 15, v2
	v_and_b32_e32 v0, 0xffff0000, v0
	v_lshl_add_u32 v0, v4, 12, v0
	v_and_b32_e32 v1, 1, v2
	v_lshl_or_b32 v0, v1, 6, v0
	v_lshl_add_u32 v176, v5, 1, v0
	v_lshlrev_b32_e32 v0, 15, v6
	v_and_b32_e32 v0, 0xffff0000, v0
	v_lshl_add_u32 v0, v7, 12, v0
	v_and_b32_e32 v1, 1, v6
	v_lshl_or_b32 v0, v1, 6, v0
	s_cmp_eq_u32 s41, 0
	s_cbranch_scc1 .Lp1d_w6_a
	s_waitcnt vmcnt(22)
	s_mov_b32 s41, 0
	s_branch .Lp1d_w6d_a
.Lp1d_w6_a:
	s_waitcnt vmcnt(6)
.Lp1d_w6d_a:
	v_lshl_add_u32 v0, v8, 1, v0
	v_mov_b32_e32 v1, v177
	v_lshl_add_u64 v[134:135], s[20:21], 0, v[0:1]
	v_lshl_add_u64 v[138:139], s[18:19], 0, v[0:1]
	v_mov_b32_e32 v0, 0
	s_xor_b64 s[16:17], s[16:17], -1
	v_lshl_add_u64 v[132:133], s[20:21], 0, v[176:177]
	v_lshl_add_u64 v[136:137], s[18:19], 0, v[176:177]
	s_mov_b32 s5, -2
	v_add_u32_e32 v140, 0, v9
	s_mov_b64 s[18:19], s[62:63]
	v_mov_b32_e32 v1, v0
	v_mov_b32_e32 v2, v0
	v_mov_b32_e32 v3, v0
	v_mov_b32_e32 v4, v0
	v_mov_b32_e32 v5, v0
	v_mov_b32_e32 v6, v0
	v_mov_b32_e32 v7, v0
	v_mov_b32_e32 v8, v0
	v_mov_b32_e32 v9, v0
	v_mov_b32_e32 v10, v0
	v_mov_b32_e32 v11, v0
	v_mov_b32_e32 v12, v0
	v_mov_b32_e32 v13, v0
	v_mov_b32_e32 v14, v0
	v_mov_b32_e32 v15, v0
	v_mov_b32_e32 v16, v0
	v_mov_b32_e32 v17, v0
	v_mov_b32_e32 v18, v0
	v_mov_b32_e32 v19, v0
	v_mov_b32_e32 v20, v0
	v_mov_b32_e32 v21, v0
	v_mov_b32_e32 v22, v0
	v_mov_b32_e32 v23, v0
	v_mov_b32_e32 v24, v0
	v_mov_b32_e32 v25, v0
	v_mov_b32_e32 v26, v0
	v_mov_b32_e32 v27, v0
	v_mov_b32_e32 v28, v0
	v_mov_b32_e32 v29, v0
	v_mov_b32_e32 v30, v0
	v_mov_b32_e32 v31, v0
	v_mov_b32_e32 v32, v0
	v_mov_b32_e32 v33, v0
	v_mov_b32_e32 v34, v0
	v_mov_b32_e32 v35, v0
	v_mov_b32_e32 v36, v0
	v_mov_b32_e32 v37, v0
	v_mov_b32_e32 v38, v0
	v_mov_b32_e32 v39, v0
	v_mov_b32_e32 v40, v0
	v_mov_b32_e32 v41, v0
	v_mov_b32_e32 v42, v0
	v_mov_b32_e32 v43, v0
	v_mov_b32_e32 v44, v0
	v_mov_b32_e32 v45, v0
	v_mov_b32_e32 v46, v0
	v_mov_b32_e32 v47, v0
	v_mov_b32_e32 v48, v0
	v_mov_b32_e32 v49, v0
	v_mov_b32_e32 v50, v0
	v_mov_b32_e32 v51, v0
	v_mov_b32_e32 v52, v0
	v_mov_b32_e32 v53, v0
	v_mov_b32_e32 v54, v0
	v_mov_b32_e32 v55, v0
	v_mov_b32_e32 v56, v0
	v_mov_b32_e32 v57, v0
	v_mov_b32_e32 v58, v0
	v_mov_b32_e32 v59, v0
	v_mov_b32_e32 v60, v0
	v_mov_b32_e32 v61, v0
	v_mov_b32_e32 v62, v0
	v_mov_b32_e32 v63, v0
	v_mov_b32_e32 v64, v0
	v_mov_b32_e32 v65, v0
	v_mov_b32_e32 v66, v0
	v_mov_b32_e32 v67, v0
	v_mov_b32_e32 v68, v0
	v_mov_b32_e32 v69, v0
	v_mov_b32_e32 v70, v0
	v_mov_b32_e32 v71, v0
	v_mov_b32_e32 v72, v0
	v_mov_b32_e32 v73, v0
	v_mov_b32_e32 v74, v0
	v_mov_b32_e32 v75, v0
	v_mov_b32_e32 v76, v0
	v_mov_b32_e32 v77, v0
	v_mov_b32_e32 v78, v0
	v_mov_b32_e32 v79, v0
	v_mov_b32_e32 v80, v0
	v_mov_b32_e32 v81, v0
	v_mov_b32_e32 v82, v0
	v_mov_b32_e32 v83, v0
	v_mov_b32_e32 v84, v0
	v_mov_b32_e32 v85, v0
	v_mov_b32_e32 v86, v0
	v_mov_b32_e32 v87, v0
	v_mov_b32_e32 v88, v0
	v_mov_b32_e32 v89, v0
	v_mov_b32_e32 v90, v0
	v_mov_b32_e32 v91, v0
	v_mov_b32_e32 v92, v0
	v_mov_b32_e32 v93, v0
	v_mov_b32_e32 v94, v0
	v_mov_b32_e32 v95, v0
	v_mov_b32_e32 v96, v0
	v_mov_b32_e32 v97, v0
	v_mov_b32_e32 v98, v0
	v_mov_b32_e32 v99, v0
	v_mov_b32_e32 v100, v0
	v_mov_b32_e32 v101, v0
	v_mov_b32_e32 v102, v0
	v_mov_b32_e32 v103, v0
	v_mov_b32_e32 v104, v0
	v_mov_b32_e32 v105, v0
	v_mov_b32_e32 v106, v0
	v_mov_b32_e32 v107, v0
	v_mov_b32_e32 v108, v0
	v_mov_b32_e32 v109, v0
	v_mov_b32_e32 v110, v0
	v_mov_b32_e32 v111, v0
	v_mov_b32_e32 v112, v0
	v_mov_b32_e32 v113, v0
	v_mov_b32_e32 v114, v0
	v_mov_b32_e32 v115, v0
	v_mov_b32_e32 v116, v0
	v_mov_b32_e32 v117, v0
	v_mov_b32_e32 v118, v0
	v_mov_b32_e32 v119, v0
	v_mov_b32_e32 v120, v0
	v_mov_b32_e32 v121, v0
	v_mov_b32_e32 v122, v0
	v_mov_b32_e32 v123, v0
	v_mov_b32_e32 v124, v0
	v_mov_b32_e32 v125, v0
	v_mov_b32_e32 v126, v0
	v_mov_b32_e32 v127, v0
	s_mov_b64 s[20:21], 0x8800100
	s_mov_b64 s[22:23], 0x8880080
	s_mov_b64 s[24:25], 0x8880100
	s_mov_b64 s[26:27], 0x8800180
	s_barrier

; template <bool NT = false>
; DEV void tile_rows_out(bf16_t* __restrict__ out0, const size_t ld, const int tid) {
; #pragma unroll
;   for (int i = 0; i < 16; ++i) {
;     const int id = i * 512 + tid, r = id >> 5, pos = id & 31, c = pos ^ (r & 31);
;     const u32x4 v = *(const u32x4*)(smem + r * 512 + pos * 16);
;     if (NT) __builtin_nontemporal_store(v, (u32x4*)(out0 + (size_t)r * ld + 8 * c)); else *(u32x4*)(out0 + (size_t)r * ld + 8 * c) = v;
;   }
;   DEV void operator()(f32x4 (&acc)[2][2][4][2], int brow, int bcol, int wr, int wc, int fr, int fq) const {
;     ...
;     __syncthreads();
;     tile_rows_out<true>(out + (size_t)brow * ld + (bcol - segstart), (size_t)ld, (wr * 4 + wc) * 64 + fq * 16 + fr);
.Lepi_lean_rows:
	s_mul_i32 s0, s4, s8
	s_sub_i32 s1, s6, s36
	s_add_i32 s0, s0, s1
	s_ashr_i32 s1, s0, 31
	s_lshl_b64 s[0:1], s[0:1], 1
	s_add_u32 s0, s14, s0
	s_addc_u32 s1, s15, s1
	v_lshrrev_b32_e32 v138, 5, v198
	v_and_b32_e32 v139, 31, v198
	v_xor_b32_e32 v139, v139, v138
	v_mul_lo_u32 v140, v138, s8
	v_lshlrev_b32_e32 v140, 1, v140
	v_lshl_add_u32 v141, v139, 4, v140
	v_xor_b32_e32 v139, 16, v139
	v_lshl_add_u32 v142, v139, 4, v140
	s_lshl_b32 s5, s8, 5
	v_add_u32_e32 v142, s5, v142
	s_lshl_b32 s5, s8, 6
	v_lshlrev_b32_e32 v143, 4, v198
	v_add_u32_e32 v144, 0x10000, v143
	s_waitcnt lgkmcnt(0)
	s_barrier
	ds_read_b128 v[64:67], v143
	ds_read_b128 v[68:71], v143 offset:8192
	ds_read_b128 v[72:75], v143 offset:16384
	ds_read_b128 v[76:79], v143 offset:24576
	ds_read_b128 v[80:83], v143 offset:32768
	ds_read_b128 v[84:87], v143 offset:40960
	ds_read_b128 v[88:91], v143 offset:49152
	ds_read_b128 v[92:95], v143 offset:57344
	ds_read_b128 v[96:99], v144
	ds_read_b128 v[100:103], v144 offset:8192
	ds_read_b128 v[104:107], v144 offset:16384
	ds_read_b128 v[108:111], v144 offset:24576
	ds_read_b128 v[112:115], v144 offset:32768
	ds_read_b128 v[116:119], v144 offset:40960
	ds_read_b128 v[120:123], v144 offset:49152
	ds_read_b128 v[124:127], v144 offset:57344
	s_waitcnt lgkmcnt(0)
	v_mov_b32_e32 v62, v141
	v_mov_b32_e32 v63, v142
	s_mov_b32 s38, s0
	s_mov_b32 s39, s1
	s_mov_b32 s40, s5
	s_mov_b32 s41, 1
	s_branch .LBB0_1555

; DEV u32x2 pk4(f32x4 v) { u32x2 r = {pk_bf16(v[0], v[1]), pk_bf16(v[2], v[3])}; return r; }
; DEV int sig4(int x) { return ((x & 1) << 1) | (x >> 1); }
;   DEV void operator()(f32x4 (&acc)[2][2][4][2], int brow, int bcol, int wr, int wc, int fr, int fq) const {
;     ...
;               const f32x4 b4 = *(const f32x4*)(bmat + (size_t)tok * 1024 + lc);
;               const int pcl = (cl & ~15) + 4 * sig4((cl >> 2) & 3);
;               if (mode == 3) {
;                 for (int j = 0; j < 4; ++j) v[j] = v[j] * scale * __expf(b4[j]);
;                 tile_put4(rl, pcl, pk4(v));
;               } else {
;                 const f32x4 bl = *(const f32x4*)(bmat + (size_t)(tok | 63) * 1024 + lc);
;                 f32x4 kd, ke;
;                 for (int j = 0; j < 4; ++j) { kd[j] = v[j] * __expf(-b4[j]); ke[j] = v[j] * __expf(bl[j] - b4[j]); }
;                 tile_put4(rl, pcl, pk4(kd));
.Lepi_lean_k4:
	global_load_dwordx4 v[128:131], v165, s[20:21]
	global_load_dwordx4 v[132:135], v165, s[20:21] offset:64
	global_load_dwordx4 v[136:139], v165, s[20:21] offset:512
	global_load_dwordx4 v[140:143], v165, s[20:21] offset:576
	s_waitcnt vmcnt(0)
	v_sub_f32_e32 v174, v128, v180
	v_sub_f32_e32 v175, v129, v181
	v_sub_f32_e32 v204, v130, v182
	v_sub_f32_e32 v205, v131, v183
	v_mul_f32_e32 v180, 0xbfb8aa3b, v180
	v_mul_f32_e32 v181, 0xbfb8aa3b, v181
	v_mul_f32_e32 v182, 0xbfb8aa3b, v182
	v_mul_f32_e32 v183, 0xbfb8aa3b, v183
	v_mul_f32_e32 v174, 0x3fb8aa3b, v174
	v_mul_f32_e32 v175, 0x3fb8aa3b, v175
	v_mul_f32_e32 v204, 0x3fb8aa3b, v204
	v_mul_f32_e32 v205, 0x3fb8aa3b, v205
	v_exp_f32_e32 v180, v180
	v_exp_f32_e32 v181, v181
	v_exp_f32_e32 v182, v182
	v_exp_f32_e32 v183, v183
	v_exp_f32_e32 v174, v174
	v_exp_f32_e32 v175, v175
	v_exp_f32_e32 v204, v204
	v_exp_f32_e32 v205, v205
	v_pk_mul_f32 v[180:181], v[124:125], v[180:181]
	v_pk_mul_f32 v[182:183], v[126:127], v[182:183]
	v_pk_mul_f32 v[124:125], v[124:125], v[174:175]
	v_pk_mul_f32 v[126:127], v[126:127], v[204:205]
	v_cvt_pk_bf16_f32 v180, v180, v181
	v_cvt_pk_bf16_f32 v181, v182, v183
	ds_write_b64 v160, v[180:181]
	v_sub_f32_e32 v174, v132, v184
	v_sub_f32_e32 v175, v133, v185
	v_sub_f32_e32 v204, v134, v186
	v_sub_f32_e32 v205, v135, v187
	v_mul_f32_e32 v184, 0xbfb8aa3b, v184
	v_mul_f32_e32 v185, 0xbfb8aa3b, v185
	v_mul_f32_e32 v186, 0xbfb8aa3b, v186
	v_mul_f32_e32 v187, 0xbfb8aa3b, v187
	v_mul_f32_e32 v174, 0x3fb8aa3b, v174
	v_mul_f32_e32 v175, 0x3fb8aa3b, v175
	v_mul_f32_e32 v204, 0x3fb8aa3b, v204
	v_mul_f32_e32 v205, 0x3fb8aa3b, v205
	v_exp_f32_e32 v184, v184
	v_exp_f32_e32 v185, v185
	v_exp_f32_e32 v186, v186
	v_exp_f32_e32 v187, v187
	v_exp_f32_e32 v174, v174
	v_exp_f32_e32 v175, v175
	v_exp_f32_e32 v204, v204
	v_exp_f32_e32 v205, v205
	v_pk_mul_f32 v[184:185], v[120:121], v[184:185]
	v_pk_mul_f32 v[186:187], v[122:123], v[186:187]
	v_pk_mul_f32 v[120:121], v[120:121], v[174:175]
	v_pk_mul_f32 v[122:123], v[122:123], v[204:205]
	v_cvt_pk_bf16_f32 v184, v184, v185
	v_cvt_pk_bf16_f32 v185, v186, v187
	ds_write_b64 v161, v[184:185]
	v_sub_f32_e32 v174, v136, v188
	v_sub_f32_e32 v175, v137, v189
	v_sub_f32_e32 v204, v138, v190
	v_sub_f32_e32 v205, v139, v191
	v_mul_f32_e32 v188, 0xbfb8aa3b, v188
	v_mul_f32_e32 v189, 0xbfb8aa3b, v189
	v_mul_f32_e32 v190, 0xbfb8aa3b, v190
	v_mul_f32_e32 v191, 0xbfb8aa3b, v191
	v_mul_f32_e32 v174, 0x3fb8aa3b, v174
	v_mul_f32_e32 v175, 0x3fb8aa3b, v175
	v_mul_f32_e32 v204, 0x3fb8aa3b, v204
	v_mul_f32_e32 v205, 0x3fb8aa3b, v205
	v_exp_f32_e32 v188, v188
	v_exp_f32_e32 v189, v189
	v_exp_f32_e32 v190, v190
	v_exp_f32_e32 v191, v191
	v_exp_f32_e32 v174, v174
	v_exp_f32_e32 v175, v175
	v_exp_f32_e32 v204, v204
	v_exp_f32_e32 v205, v205
	v_pk_mul_f32 v[188:189], v[116:117], v[188:189]
	v_pk_mul_f32 v[190:191], v[118:119], v[190:191]
	v_pk_mul_f32 v[116:117], v[116:117], v[174:175]
	v_pk_mul_f32 v[118:119], v[118:119], v[204:205]
	v_cvt_pk_bf16_f32 v188, v188, v189
	v_cvt_pk_bf16_f32 v189, v190, v191
	ds_write_b64 v160, v[188:189] offset:256
	v_sub_f32_e32 v174, v140, v192
	v_sub_f32_e32 v175, v141, v193
	v_sub_f32_e32 v204, v142, v194
	v_sub_f32_e32 v205, v143, v195
	v_mul_f32_e32 v192, 0xbfb8aa3b, v192
	v_mul_f32_e32 v193, 0xbfb8aa3b, v193
	v_mul_f32_e32 v194, 0xbfb8aa3b, v194
	v_mul_f32_e32 v195, 0xbfb8aa3b, v195
	v_mul_f32_e32 v174, 0x3fb8aa3b, v174
	v_mul_f32_e32 v175, 0x3fb8aa3b, v175
	v_mul_f32_e32 v204, 0x3fb8aa3b, v204
	v_mul_f32_e32 v205, 0x3fb8aa3b, v205
	v_exp_f32_e32 v192, v192
	v_exp_f32_e32 v193, v193
	v_exp_f32_e32 v194, v194
	v_exp_f32_e32 v195, v195
	v_exp_f32_e32 v174, v174
	v_exp_f32_e32 v175, v175
	v_exp_f32_e32 v204, v204
	v_exp_f32_e32 v205, v205
	v_pk_mul_f32 v[192:193], v[112:113], v[192:193]
	v_pk_mul_f32 v[194:195], v[114:115], v[194:195]
	v_pk_mul_f32 v[112:113], v[112:113], v[174:175]
	v_pk_mul_f32 v[114:115], v[114:115], v[204:205]
	v_cvt_pk_bf16_f32 v192, v192, v193
	v_cvt_pk_bf16_f32 v193, v194, v195
	ds_write_b64 v161, v[192:193] offset:256
	v_sub_f32_e32 v174, v128, v206
	v_sub_f32_e32 v175, v129, v207
	v_sub_f32_e32 v204, v130, v208
	v_sub_f32_e32 v205, v131, v209
	v_mul_f32_e32 v206, 0xbfb8aa3b, v206
	v_mul_f32_e32 v207, 0xbfb8aa3b, v207
	v_mul_f32_e32 v208, 0xbfb8aa3b, v208
	v_mul_f32_e32 v209, 0xbfb8aa3b, v209
	v_mul_f32_e32 v174, 0x3fb8aa3b, v174
	v_mul_f32_e32 v175, 0x3fb8aa3b, v175
	v_mul_f32_e32 v204, 0x3fb8aa3b, v204
	v_mul_f32_e32 v205, 0x3fb8aa3b, v205
	v_exp_f32_e32 v206, v206
	v_exp_f32_e32 v207, v207
	v_exp_f32_e32 v208, v208
	v_exp_f32_e32 v209, v209
	v_exp_f32_e32 v174, v174
	v_exp_f32_e32 v175, v175
	v_exp_f32_e32 v204, v204
	v_exp_f32_e32 v205, v205
	v_pk_mul_f32 v[206:207], v[108:109], v[206:207]
	v_pk_mul_f32 v[208:209], v[110:111], v[208:209]
	v_pk_mul_f32 v[108:109], v[108:109], v[174:175]
	v_pk_mul_f32 v[110:111], v[110:111], v[204:205]
	v_cvt_pk_bf16_f32 v206, v206, v207
	v_cvt_pk_bf16_f32 v207, v208, v209
	ds_write_b64 v160, v[206:207] offset:8448
	v_sub_f32_e32 v174, v132, v210
	v_sub_f32_e32 v175, v133, v211
	v_sub_f32_e32 v204, v134, v212
	v_sub_f32_e32 v205, v135, v213
	v_mul_f32_e32 v210, 0xbfb8aa3b, v210
	v_mul_f32_e32 v211, 0xbfb8aa3b, v211
	v_mul_f32_e32 v212, 0xbfb8aa3b, v212
	v_mul_f32_e32 v213, 0xbfb8aa3b, v213
	v_mul_f32_e32 v174, 0x3fb8aa3b, v174
	v_mul_f32_e32 v175, 0x3fb8aa3b, v175
	v_mul_f32_e32 v204, 0x3fb8aa3b, v204
	v_mul_f32_e32 v205, 0x3fb8aa3b, v205
	v_exp_f32_e32 v210, v210
	v_exp_f32_e32 v211, v211
	v_exp_f32_e32 v212, v212
	v_exp_f32_e32 v213, v213
	v_exp_f32_e32 v174, v174
	v_exp_f32_e32 v175, v175
	v_exp_f32_e32 v204, v204
	v_exp_f32_e32 v205, v205
; DEV u32x2 pk4(f32x4 v) { u32x2 r = {pk_bf16(v[0], v[1]), pk_bf16(v[2], v[3])}; return r; }
; DEV int sig4(int x) { return ((x & 1) << 1) | (x >> 1); }
;   DEV void operator()(f32x4 (&acc)[2][2][4][2], int brow, int bcol, int wr, int wc, int fr, int fq) const {
;     ...
;               const f32x4 b4 = *(const f32x4*)(bmat + (size_t)tok * 1024 + lc);
;               const int pcl = (cl & ~15) + 4 * sig4((cl >> 2) & 3);
;               if (mode == 3) {
;                 for (int j = 0; j < 4; ++j) v[j] = v[j] * scale * __expf(b4[j]);
;                 tile_put4(rl, pcl, pk4(v));
;               } else {
;                 const f32x4 bl = *(const f32x4*)(bmat + (size_t)(tok | 63) * 1024 + lc);
;                 f32x4 kd, ke;
;                 for (int j = 0; j < 4; ++j) { kd[j] = v[j] * __expf(-b4[j]); ke[j] = v[j] * __expf(bl[j] - b4[j]); }
;                 tile_put4(rl, pcl, pk4(kd));
	v_pk_mul_f32 v[210:211], v[104:105], v[210:211]
	v_pk_mul_f32 v[212:213], v[106:107], v[212:213]
	v_pk_mul_f32 v[104:105], v[104:105], v[174:175]
	v_pk_mul_f32 v[106:107], v[106:107], v[204:205]
	v_cvt_pk_bf16_f32 v210, v210, v211
	v_cvt_pk_bf16_f32 v211, v212, v213
	ds_write_b64 v161, v[210:211] offset:8448
	v_sub_f32_e32 v174, v136, v214
	v_sub_f32_e32 v175, v137, v215
	v_sub_f32_e32 v204, v138, v216
	v_sub_f32_e32 v205, v139, v217
	v_mul_f32_e32 v214, 0xbfb8aa3b, v214
	v_mul_f32_e32 v215, 0xbfb8aa3b, v215
	v_mul_f32_e32 v216, 0xbfb8aa3b, v216
	v_mul_f32_e32 v217, 0xbfb8aa3b, v217
	v_mul_f32_e32 v174, 0x3fb8aa3b, v174
	v_mul_f32_e32 v175, 0x3fb8aa3b, v175
	v_mul_f32_e32 v204, 0x3fb8aa3b, v204
	v_mul_f32_e32 v205, 0x3fb8aa3b, v205
	v_exp_f32_e32 v214, v214
	v_exp_f32_e32 v215, v215
	v_exp_f32_e32 v216, v216
	v_exp_f32_e32 v217, v217
	v_exp_f32_e32 v174, v174
	v_exp_f32_e32 v175, v175
	v_exp_f32_e32 v204, v204
	v_exp_f32_e32 v205, v205
	v_pk_mul_f32 v[214:215], v[100:101], v[214:215]
	v_pk_mul_f32 v[216:217], v[102:103], v[216:217]
	v_pk_mul_f32 v[100:101], v[100:101], v[174:175]
	v_pk_mul_f32 v[102:103], v[102:103], v[204:205]
	v_cvt_pk_bf16_f32 v214, v214, v215
	v_cvt_pk_bf16_f32 v215, v216, v217
	ds_write_b64 v160, v[214:215] offset:8192
	v_sub_f32_e32 v174, v140, v224
	v_sub_f32_e32 v175, v141, v225
	v_sub_f32_e32 v204, v142, v226
	v_sub_f32_e32 v205, v143, v227
	v_mul_f32_e32 v224, 0xbfb8aa3b, v224
	v_mul_f32_e32 v225, 0xbfb8aa3b, v225
	v_mul_f32_e32 v226, 0xbfb8aa3b, v226
	v_mul_f32_e32 v227, 0xbfb8aa3b, v227
	v_mul_f32_e32 v174, 0x3fb8aa3b, v174
	v_mul_f32_e32 v175, 0x3fb8aa3b, v175
	v_mul_f32_e32 v204, 0x3fb8aa3b, v204
	v_mul_f32_e32 v205, 0x3fb8aa3b, v205
	v_exp_f32_e32 v224, v224
	v_exp_f32_e32 v225, v225
	v_exp_f32_e32 v226, v226
	v_exp_f32_e32 v227, v227
	v_exp_f32_e32 v174, v174
	v_exp_f32_e32 v175, v175
	v_exp_f32_e32 v204, v204
	v_exp_f32_e32 v205, v205
	v_pk_mul_f32 v[224:225], v[96:97], v[224:225]
	v_pk_mul_f32 v[226:227], v[98:99], v[226:227]
	v_pk_mul_f32 v[96:97], v[96:97], v[174:175]
	v_pk_mul_f32 v[98:99], v[98:99], v[204:205]
	v_cvt_pk_bf16_f32 v224, v224, v225
	v_cvt_pk_bf16_f32 v225, v226, v227
	ds_write_b64 v161, v[224:225] offset:8192
	v_sub_f32_e32 v174, v128, v228
	v_sub_f32_e32 v175, v129, v229
	v_sub_f32_e32 v204, v130, v230
	v_sub_f32_e32 v205, v131, v231
	v_mul_f32_e32 v228, 0xbfb8aa3b, v228
	v_mul_f32_e32 v229, 0xbfb8aa3b, v229
	v_mul_f32_e32 v230, 0xbfb8aa3b, v230
	v_mul_f32_e32 v231, 0xbfb8aa3b, v231
	v_mul_f32_e32 v174, 0x3fb8aa3b, v174
	v_mul_f32_e32 v175, 0x3fb8aa3b, v175
	v_mul_f32_e32 v204, 0x3fb8aa3b, v204
	v_mul_f32_e32 v205, 0x3fb8aa3b, v205
	v_exp_f32_e32 v228, v228
	v_exp_f32_e32 v229, v229
	v_exp_f32_e32 v230, v230
	v_exp_f32_e32 v231, v231
	v_exp_f32_e32 v174, v174
	v_exp_f32_e32 v175, v175
	v_exp_f32_e32 v204, v204
	v_exp_f32_e32 v205, v205
	v_pk_mul_f32 v[228:229], v[92:93], v[228:229]
	v_pk_mul_f32 v[230:231], v[94:95], v[230:231]
	v_pk_mul_f32 v[92:93], v[92:93], v[174:175]
	v_pk_mul_f32 v[94:95], v[94:95], v[204:205]
	v_cvt_pk_bf16_f32 v228, v228, v229
	v_cvt_pk_bf16_f32 v229, v230, v231
	ds_write_b64 v160, v[228:229] offset:16384
	v_sub_f32_e32 v174, v132, v232
	v_sub_f32_e32 v175, v133, v233
	v_sub_f32_e32 v204, v134, v234
	v_sub_f32_e32 v205, v135, v235
	v_mul_f32_e32 v232, 0xbfb8aa3b, v232
	v_mul_f32_e32 v233, 0xbfb8aa3b, v233
	v_mul_f32_e32 v234, 0xbfb8aa3b, v234
	v_mul_f32_e32 v235, 0xbfb8aa3b, v235
	v_mul_f32_e32 v174, 0x3fb8aa3b, v174
	v_mul_f32_e32 v175, 0x3fb8aa3b, v175
	v_mul_f32_e32 v204, 0x3fb8aa3b, v204
	v_mul_f32_e32 v205, 0x3fb8aa3b, v205
	v_exp_f32_e32 v232, v232
	v_exp_f32_e32 v233, v233
	v_exp_f32_e32 v234, v234
	v_exp_f32_e32 v235, v235
	v_exp_f32_e32 v174, v174
	v_exp_f32_e32 v175, v175
	v_exp_f32_e32 v204, v204
	v_exp_f32_e32 v205, v205
	v_pk_mul_f32 v[232:233], v[88:89], v[232:233]
	v_pk_mul_f32 v[234:235], v[90:91], v[234:235]
	v_pk_mul_f32 v[88:89], v[88:89], v[174:175]
	v_pk_mul_f32 v[90:91], v[90:91], v[204:205]
	v_cvt_pk_bf16_f32 v232, v232, v233
	v_cvt_pk_bf16_f32 v233, v234, v235
	ds_write_b64 v161, v[232:233] offset:16384
	v_sub_f32_e32 v174, v136, v236
	v_sub_f32_e32 v175, v137, v237
	v_sub_f32_e32 v204, v138, v238
	v_sub_f32_e32 v205, v139, v239
	v_mul_f32_e32 v236, 0xbfb8aa3b, v236
	v_mul_f32_e32 v237, 0xbfb8aa3b, v237
	v_mul_f32_e32 v238, 0xbfb8aa3b, v238
	v_mul_f32_e32 v239, 0xbfb8aa3b, v239
	v_mul_f32_e32 v174, 0x3fb8aa3b, v174
	v_mul_f32_e32 v175, 0x3fb8aa3b, v175
	v_mul_f32_e32 v204, 0x3fb8aa3b, v204
	v_mul_f32_e32 v205, 0x3fb8aa3b, v205
	v_exp_f32_e32 v236, v236
	v_exp_f32_e32 v237, v237
	v_exp_f32_e32 v238, v238
	v_exp_f32_e32 v239, v239
	v_exp_f32_e32 v174, v174
	v_exp_f32_e32 v175, v175
	v_exp_f32_e32 v204, v204
	v_exp_f32_e32 v205, v205
	v_pk_mul_f32 v[236:237], v[84:85], v[236:237]
	v_pk_mul_f32 v[238:239], v[86:87], v[238:239]
	v_pk_mul_f32 v[84:85], v[84:85], v[174:175]
	v_pk_mul_f32 v[86:87], v[86:87], v[204:205]
	v_cvt_pk_bf16_f32 v236, v236, v237
	v_cvt_pk_bf16_f32 v237, v238, v239
	ds_write_b64 v160, v[236:237] offset:16640
	v_sub_f32_e32 v174, v140, v240
	v_sub_f32_e32 v175, v141, v241
	v_sub_f32_e32 v204, v142, v242
	v_sub_f32_e32 v205, v143, v243
	v_mul_f32_e32 v240, 0xbfb8aa3b, v240
	v_mul_f32_e32 v241, 0xbfb8aa3b, v241
	v_mul_f32_e32 v242, 0xbfb8aa3b, v242
	v_mul_f32_e32 v243, 0xbfb8aa3b, v243
	v_mul_f32_e32 v174, 0x3fb8aa3b, v174
	v_mul_f32_e32 v175, 0x3fb8aa3b, v175
	v_mul_f32_e32 v204, 0x3fb8aa3b, v204
	v_mul_f32_e32 v205, 0x3fb8aa3b, v205
	v_exp_f32_e32 v240, v240
	v_exp_f32_e32 v241, v241
	v_exp_f32_e32 v242, v242
	v_exp_f32_e32 v243, v243
	v_exp_f32_e32 v174, v174
	v_exp_f32_e32 v175, v175
	v_exp_f32_e32 v204, v204
; DEV u32x2 pk4(f32x4 v) { u32x2 r = {pk_bf16(v[0], v[1]), pk_bf16(v[2], v[3])}; return r; }
; DEV int sig4(int x) { return ((x & 1) << 1) | (x >> 1); }
;   DEV void operator()(f32x4 (&acc)[2][2][4][2], int brow, int bcol, int wr, int wc, int fr, int fq) const {
;     ...
;               const f32x4 b4 = *(const f32x4*)(bmat + (size_t)tok * 1024 + lc);
;               const int pcl = (cl & ~15) + 4 * sig4((cl >> 2) & 3);
;               if (mode == 3) {
;                 for (int j = 0; j < 4; ++j) v[j] = v[j] * scale * __expf(b4[j]);
;                 tile_put4(rl, pcl, pk4(v));
;               } else {
;                 const f32x4 bl = *(const f32x4*)(bmat + (size_t)(tok | 63) * 1024 + lc);
;                 f32x4 kd, ke;
;                 for (int j = 0; j < 4; ++j) { kd[j] = v[j] * __expf(-b4[j]); ke[j] = v[j] * __expf(bl[j] - b4[j]); }
;                 tile_put4(rl, pcl, pk4(kd));
	v_exp_f32_e32 v205, v205
	v_pk_mul_f32 v[240:241], v[80:81], v[240:241]
	v_pk_mul_f32 v[242:243], v[82:83], v[242:243]
	v_pk_mul_f32 v[80:81], v[80:81], v[174:175]
	v_pk_mul_f32 v[82:83], v[82:83], v[204:205]
	v_cvt_pk_bf16_f32 v240, v240, v241
	v_cvt_pk_bf16_f32 v241, v242, v243
	ds_write_b64 v161, v[240:241] offset:16640
	v_sub_f32_e32 v174, v128, v244
	v_sub_f32_e32 v175, v129, v245
	v_sub_f32_e32 v204, v130, v246
	v_sub_f32_e32 v205, v131, v247
	v_mul_f32_e32 v244, 0xbfb8aa3b, v244
	v_mul_f32_e32 v245, 0xbfb8aa3b, v245
	v_mul_f32_e32 v246, 0xbfb8aa3b, v246
	v_mul_f32_e32 v247, 0xbfb8aa3b, v247
	v_mul_f32_e32 v174, 0x3fb8aa3b, v174
	v_mul_f32_e32 v175, 0x3fb8aa3b, v175
	v_mul_f32_e32 v204, 0x3fb8aa3b, v204
	v_mul_f32_e32 v205, 0x3fb8aa3b, v205
	v_exp_f32_e32 v244, v244
	v_exp_f32_e32 v245, v245
	v_exp_f32_e32 v246, v246
	v_exp_f32_e32 v247, v247
	v_exp_f32_e32 v174, v174
	v_exp_f32_e32 v175, v175
	v_exp_f32_e32 v204, v204
	v_exp_f32_e32 v205, v205
	v_pk_mul_f32 v[244:245], v[76:77], v[244:245]
	v_pk_mul_f32 v[246:247], v[78:79], v[246:247]
	v_pk_mul_f32 v[76:77], v[76:77], v[174:175]
	v_pk_mul_f32 v[78:79], v[78:79], v[204:205]
	v_cvt_pk_bf16_f32 v244, v244, v245
	v_cvt_pk_bf16_f32 v245, v246, v247
	ds_write_b64 v160, v[244:245] offset:24832
	v_sub_f32_e32 v174, v132, v248
	v_sub_f32_e32 v175, v133, v249
	v_sub_f32_e32 v204, v134, v250
	v_sub_f32_e32 v205, v135, v251
	v_mul_f32_e32 v248, 0xbfb8aa3b, v248
	v_mul_f32_e32 v249, 0xbfb8aa3b, v249
	v_mul_f32_e32 v250, 0xbfb8aa3b, v250
	v_mul_f32_e32 v251, 0xbfb8aa3b, v251
	v_mul_f32_e32 v174, 0x3fb8aa3b, v174
	v_mul_f32_e32 v175, 0x3fb8aa3b, v175
	v_mul_f32_e32 v204, 0x3fb8aa3b, v204
	v_mul_f32_e32 v205, 0x3fb8aa3b, v205
	v_exp_f32_e32 v248, v248
	v_exp_f32_e32 v249, v249
	v_exp_f32_e32 v250, v250
	v_exp_f32_e32 v251, v251
	v_exp_f32_e32 v174, v174
	v_exp_f32_e32 v175, v175
	v_exp_f32_e32 v204, v204
	v_exp_f32_e32 v205, v205
	v_pk_mul_f32 v[248:249], v[72:73], v[248:249]
	v_pk_mul_f32 v[250:251], v[74:75], v[250:251]
	v_pk_mul_f32 v[72:73], v[72:73], v[174:175]
	v_pk_mul_f32 v[74:75], v[74:75], v[204:205]
	v_cvt_pk_bf16_f32 v248, v248, v249
	v_cvt_pk_bf16_f32 v249, v250, v251
	ds_write_b64 v161, v[248:249] offset:24832
	v_sub_f32_e32 v174, v136, v166
	v_sub_f32_e32 v175, v137, v167
	v_sub_f32_e32 v204, v138, v168
	v_sub_f32_e32 v205, v139, v169
	v_mul_f32_e32 v166, 0xbfb8aa3b, v166
	v_mul_f32_e32 v167, 0xbfb8aa3b, v167
	v_mul_f32_e32 v168, 0xbfb8aa3b, v168
	v_mul_f32_e32 v169, 0xbfb8aa3b, v169
	v_mul_f32_e32 v174, 0x3fb8aa3b, v174
	v_mul_f32_e32 v175, 0x3fb8aa3b, v175
	v_mul_f32_e32 v204, 0x3fb8aa3b, v204
	v_mul_f32_e32 v205, 0x3fb8aa3b, v205
	v_exp_f32_e32 v166, v166
	v_exp_f32_e32 v167, v167
	v_exp_f32_e32 v168, v168
	v_exp_f32_e32 v169, v169
	v_exp_f32_e32 v174, v174
	v_exp_f32_e32 v175, v175
	v_exp_f32_e32 v204, v204
	v_exp_f32_e32 v205, v205
	v_pk_mul_f32 v[166:167], v[68:69], v[166:167]
	v_pk_mul_f32 v[168:169], v[70:71], v[168:169]
	v_pk_mul_f32 v[68:69], v[68:69], v[174:175]
	v_pk_mul_f32 v[70:71], v[70:71], v[204:205]
	v_cvt_pk_bf16_f32 v166, v166, v167
	v_cvt_pk_bf16_f32 v167, v168, v169
	ds_write_b64 v160, v[166:167] offset:24576
	v_sub_f32_e32 v174, v140, v170
	v_sub_f32_e32 v175, v141, v171
	v_sub_f32_e32 v204, v142, v172
	v_sub_f32_e32 v205, v143, v173
	v_mul_f32_e32 v170, 0xbfb8aa3b, v170
	v_mul_f32_e32 v171, 0xbfb8aa3b, v171
	v_mul_f32_e32 v172, 0xbfb8aa3b, v172
	v_mul_f32_e32 v173, 0xbfb8aa3b, v173
	v_mul_f32_e32 v174, 0x3fb8aa3b, v174
	v_mul_f32_e32 v175, 0x3fb8aa3b, v175
	v_mul_f32_e32 v204, 0x3fb8aa3b, v204
	v_mul_f32_e32 v205, 0x3fb8aa3b, v205
	v_exp_f32_e32 v170, v170
	v_exp_f32_e32 v171, v171
	v_exp_f32_e32 v172, v172
	v_exp_f32_e32 v173, v173
	v_exp_f32_e32 v174, v174
	v_exp_f32_e32 v175, v175
	v_exp_f32_e32 v204, v204
	v_exp_f32_e32 v205, v205
	v_pk_mul_f32 v[170:171], v[64:65], v[170:171]
	v_pk_mul_f32 v[172:173], v[66:67], v[172:173]
	v_pk_mul_f32 v[64:65], v[64:65], v[174:175]
	v_pk_mul_f32 v[66:67], v[66:67], v[204:205]
	v_cvt_pk_bf16_f32 v170, v170, v171
	v_cvt_pk_bf16_f32 v171, v172, v173
	ds_write_b64 v161, v[170:171] offset:24576
	v_add_u32_e32 v164, 0x40000, v164
	global_load_dwordx4 v[180:183], v164, s[20:21]
	global_load_dwordx4 v[184:187], v164, s[20:21] offset:64
	global_load_dwordx4 v[188:191], v164, s[20:21] offset:512
	global_load_dwordx4 v[192:195], v164, s[20:21] offset:576
	v_add_u32_e32 v164, 0x10000, v164
	global_load_dwordx4 v[206:209], v164, s[20:21]
	global_load_dwordx4 v[210:213], v164, s[20:21] offset:64
	global_load_dwordx4 v[214:217], v164, s[20:21] offset:512
	global_load_dwordx4 v[224:227], v164, s[20:21] offset:576
	v_add_u32_e32 v164, 0x10000, v164
	global_load_dwordx4 v[228:231], v164, s[20:21]
	global_load_dwordx4 v[232:235], v164, s[20:21] offset:64
	global_load_dwordx4 v[236:239], v164, s[20:21] offset:512
	global_load_dwordx4 v[240:243], v164, s[20:21] offset:576
	v_add_u32_e32 v164, 0x10000, v164
	global_load_dwordx4 v[244:247], v164, s[20:21]
	global_load_dwordx4 v[248:251], v164, s[20:21] offset:64
	global_load_dwordx4 v[166:169], v164, s[20:21] offset:512
	global_load_dwordx4 v[170:173], v164, s[20:21] offset:576
	v_add_u32_e32 v164, 0x10000, v164
	v_add_u32_e32 v165, 0x80000, v165
	global_load_dwordx4 v[144:147], v165, s[20:21]
	global_load_dwordx4 v[148:151], v165, s[20:21] offset:64
	global_load_dwordx4 v[152:155], v165, s[20:21] offset:512
	global_load_dwordx4 v[156:159], v165, s[20:21] offset:576
	s_waitcnt vmcnt(0)
; DEV u32x2 pk4(f32x4 v) { u32x2 r = {pk_bf16(v[0], v[1]), pk_bf16(v[2], v[3])}; return r; }
; DEV int sig4(int x) { return ((x & 1) << 1) | (x >> 1); }
;   DEV void operator()(f32x4 (&acc)[2][2][4][2], int brow, int bcol, int wr, int wc, int fr, int fq) const {
;     ...
;               const f32x4 b4 = *(const f32x4*)(bmat + (size_t)tok * 1024 + lc);
;               const int pcl = (cl & ~15) + 4 * sig4((cl >> 2) & 3);
;               if (mode == 3) {
;                 for (int j = 0; j < 4; ++j) v[j] = v[j] * scale * __expf(b4[j]);
;                 tile_put4(rl, pcl, pk4(v));
;               } else {
;                 const f32x4 bl = *(const f32x4*)(bmat + (size_t)(tok | 63) * 1024 + lc);
;                 f32x4 kd, ke;
;                 for (int j = 0; j < 4; ++j) { kd[j] = v[j] * __expf(-b4[j]); ke[j] = v[j] * __expf(bl[j] - b4[j]); }
;                 tile_put4(rl, pcl, pk4(kd));
	v_sub_f32_e32 v174, v144, v180
	v_sub_f32_e32 v175, v145, v181
	v_sub_f32_e32 v204, v146, v182
	v_sub_f32_e32 v205, v147, v183
	v_mul_f32_e32 v180, 0xbfb8aa3b, v180
	v_mul_f32_e32 v181, 0xbfb8aa3b, v181
	v_mul_f32_e32 v182, 0xbfb8aa3b, v182
	v_mul_f32_e32 v183, 0xbfb8aa3b, v183
	v_mul_f32_e32 v174, 0x3fb8aa3b, v174
	v_mul_f32_e32 v175, 0x3fb8aa3b, v175
	v_mul_f32_e32 v204, 0x3fb8aa3b, v204
	v_mul_f32_e32 v205, 0x3fb8aa3b, v205
	v_exp_f32_e32 v180, v180
	v_exp_f32_e32 v181, v181
	v_exp_f32_e32 v182, v182
	v_exp_f32_e32 v183, v183
	v_exp_f32_e32 v174, v174
	v_exp_f32_e32 v175, v175
	v_exp_f32_e32 v204, v204
	v_exp_f32_e32 v205, v205
	v_pk_mul_f32 v[180:181], v[60:61], v[180:181]
	v_pk_mul_f32 v[182:183], v[62:63], v[182:183]
	v_pk_mul_f32 v[60:61], v[60:61], v[174:175]
	v_pk_mul_f32 v[62:63], v[62:63], v[204:205]
	v_cvt_pk_bf16_f32 v180, v180, v181
	v_cvt_pk_bf16_f32 v181, v182, v183
	ds_write_b64 v162, v[180:181]
	v_sub_f32_e32 v174, v148, v184
	v_sub_f32_e32 v175, v149, v185
	v_sub_f32_e32 v204, v150, v186
	v_sub_f32_e32 v205, v151, v187
	v_mul_f32_e32 v184, 0xbfb8aa3b, v184
	v_mul_f32_e32 v185, 0xbfb8aa3b, v185
	v_mul_f32_e32 v186, 0xbfb8aa3b, v186
	v_mul_f32_e32 v187, 0xbfb8aa3b, v187
	v_mul_f32_e32 v174, 0x3fb8aa3b, v174
	v_mul_f32_e32 v175, 0x3fb8aa3b, v175
	v_mul_f32_e32 v204, 0x3fb8aa3b, v204
	v_mul_f32_e32 v205, 0x3fb8aa3b, v205
	v_exp_f32_e32 v184, v184
	v_exp_f32_e32 v185, v185
	v_exp_f32_e32 v186, v186
	v_exp_f32_e32 v187, v187
	v_exp_f32_e32 v174, v174
	v_exp_f32_e32 v175, v175
	v_exp_f32_e32 v204, v204
	v_exp_f32_e32 v205, v205
	v_pk_mul_f32 v[184:185], v[56:57], v[184:185]
	v_pk_mul_f32 v[186:187], v[58:59], v[186:187]
	v_pk_mul_f32 v[56:57], v[56:57], v[174:175]
	v_pk_mul_f32 v[58:59], v[58:59], v[204:205]
	v_cvt_pk_bf16_f32 v184, v184, v185
	v_cvt_pk_bf16_f32 v185, v186, v187
	ds_write_b64 v163, v[184:185]
	v_sub_f32_e32 v174, v152, v188
	v_sub_f32_e32 v175, v153, v189
	v_sub_f32_e32 v204, v154, v190
	v_sub_f32_e32 v205, v155, v191
	v_mul_f32_e32 v188, 0xbfb8aa3b, v188
	v_mul_f32_e32 v189, 0xbfb8aa3b, v189
	v_mul_f32_e32 v190, 0xbfb8aa3b, v190
	v_mul_f32_e32 v191, 0xbfb8aa3b, v191
	v_mul_f32_e32 v174, 0x3fb8aa3b, v174
	v_mul_f32_e32 v175, 0x3fb8aa3b, v175
	v_mul_f32_e32 v204, 0x3fb8aa3b, v204
	v_mul_f32_e32 v205, 0x3fb8aa3b, v205
	v_exp_f32_e32 v188, v188
	v_exp_f32_e32 v189, v189
	v_exp_f32_e32 v190, v190
	v_exp_f32_e32 v191, v191
	v_exp_f32_e32 v174, v174
	v_exp_f32_e32 v175, v175
	v_exp_f32_e32 v204, v204
	v_exp_f32_e32 v205, v205
	v_pk_mul_f32 v[188:189], v[52:53], v[188:189]
	v_pk_mul_f32 v[190:191], v[54:55], v[190:191]
	v_pk_mul_f32 v[52:53], v[52:53], v[174:175]
	v_pk_mul_f32 v[54:55], v[54:55], v[204:205]
	v_cvt_pk_bf16_f32 v188, v188, v189
	v_cvt_pk_bf16_f32 v189, v190, v191
	ds_write_b64 v162, v[188:189] offset:256
	v_sub_f32_e32 v174, v156, v192
	v_sub_f32_e32 v175, v157, v193
	v_sub_f32_e32 v204, v158, v194
	v_sub_f32_e32 v205, v159, v195
	v_mul_f32_e32 v192, 0xbfb8aa3b, v192
	v_mul_f32_e32 v193, 0xbfb8aa3b, v193
	v_mul_f32_e32 v194, 0xbfb8aa3b, v194
	v_mul_f32_e32 v195, 0xbfb8aa3b, v195
	v_mul_f32_e32 v174, 0x3fb8aa3b, v174
	v_mul_f32_e32 v175, 0x3fb8aa3b, v175
	v_mul_f32_e32 v204, 0x3fb8aa3b, v204
	v_mul_f32_e32 v205, 0x3fb8aa3b, v205
	v_exp_f32_e32 v192, v192
	v_exp_f32_e32 v193, v193
	v_exp_f32_e32 v194, v194
	v_exp_f32_e32 v195, v195
	v_exp_f32_e32 v174, v174
	v_exp_f32_e32 v175, v175
	v_exp_f32_e32 v204, v204
	v_exp_f32_e32 v205, v205
	v_pk_mul_f32 v[192:193], v[48:49], v[192:193]
	v_pk_mul_f32 v[194:195], v[50:51], v[194:195]
	v_pk_mul_f32 v[48:49], v[48:49], v[174:175]
	v_pk_mul_f32 v[50:51], v[50:51], v[204:205]
	v_cvt_pk_bf16_f32 v192, v192, v193
	v_cvt_pk_bf16_f32 v193, v194, v195
	ds_write_b64 v163, v[192:193] offset:256
	v_sub_f32_e32 v174, v144, v206
	v_sub_f32_e32 v175, v145, v207
	v_sub_f32_e32 v204, v146, v208
	v_sub_f32_e32 v205, v147, v209
	v_mul_f32_e32 v206, 0xbfb8aa3b, v206
	v_mul_f32_e32 v207, 0xbfb8aa3b, v207
	v_mul_f32_e32 v208, 0xbfb8aa3b, v208
	v_mul_f32_e32 v209, 0xbfb8aa3b, v209
	v_mul_f32_e32 v174, 0x3fb8aa3b, v174
	v_mul_f32_e32 v175, 0x3fb8aa3b, v175
	v_mul_f32_e32 v204, 0x3fb8aa3b, v204
	v_mul_f32_e32 v205, 0x3fb8aa3b, v205
	v_exp_f32_e32 v206, v206
	v_exp_f32_e32 v207, v207
	v_exp_f32_e32 v208, v208
	v_exp_f32_e32 v209, v209
	v_exp_f32_e32 v174, v174
	v_exp_f32_e32 v175, v175
	v_exp_f32_e32 v204, v204
	v_exp_f32_e32 v205, v205
	v_pk_mul_f32 v[206:207], v[44:45], v[206:207]
	v_pk_mul_f32 v[208:209], v[46:47], v[208:209]
	v_pk_mul_f32 v[44:45], v[44:45], v[174:175]
	v_pk_mul_f32 v[46:47], v[46:47], v[204:205]
	v_cvt_pk_bf16_f32 v206, v206, v207
	v_cvt_pk_bf16_f32 v207, v208, v209
	ds_write_b64 v162, v[206:207] offset:8448
	v_sub_f32_e32 v174, v148, v210
	v_sub_f32_e32 v175, v149, v211
	v_sub_f32_e32 v204, v150, v212
	v_sub_f32_e32 v205, v151, v213
	v_mul_f32_e32 v210, 0xbfb8aa3b, v210
	v_mul_f32_e32 v211, 0xbfb8aa3b, v211
	v_mul_f32_e32 v212, 0xbfb8aa3b, v212
	v_mul_f32_e32 v213, 0xbfb8aa3b, v213
	v_mul_f32_e32 v174, 0x3fb8aa3b, v174
	v_mul_f32_e32 v175, 0x3fb8aa3b, v175
	v_mul_f32_e32 v204, 0x3fb8aa3b, v204
	v_mul_f32_e32 v205, 0x3fb8aa3b, v205
	v_exp_f32_e32 v210, v210
	v_exp_f32_e32 v211, v211
	v_exp_f32_e32 v212, v212
	v_exp_f32_e32 v213, v213
	v_exp_f32_e32 v174, v174
	v_exp_f32_e32 v175, v175
	v_exp_f32_e32 v204, v204
	v_exp_f32_e32 v205, v205
	v_pk_mul_f32 v[210:211], v[40:41], v[210:211]
	v_pk_mul_f32 v[212:213], v[42:43], v[212:213]
	v_pk_mul_f32 v[40:41], v[40:41], v[174:175]
	v_pk_mul_f32 v[42:43], v[42:43], v[204:205]
	v_cvt_pk_bf16_f32 v210, v210, v211
	v_cvt_pk_bf16_f32 v211, v212, v213
	ds_write_b64 v163, v[210:211] offset:8448
	v_sub_f32_e32 v174, v152, v214
; DEV u32x2 pk4(f32x4 v) { u32x2 r = {pk_bf16(v[0], v[1]), pk_bf16(v[2], v[3])}; return r; }
; DEV int sig4(int x) { return ((x & 1) << 1) | (x >> 1); }
;   DEV void operator()(f32x4 (&acc)[2][2][4][2], int brow, int bcol, int wr, int wc, int fr, int fq) const {
;     ...
;               const f32x4 b4 = *(const f32x4*)(bmat + (size_t)tok * 1024 + lc);
;               const int pcl = (cl & ~15) + 4 * sig4((cl >> 2) & 3);
;               if (mode == 3) {
;                 for (int j = 0; j < 4; ++j) v[j] = v[j] * scale * __expf(b4[j]);
;                 tile_put4(rl, pcl, pk4(v));
;               } else {
;                 const f32x4 bl = *(const f32x4*)(bmat + (size_t)(tok | 63) * 1024 + lc);
;                 f32x4 kd, ke;
;                 for (int j = 0; j < 4; ++j) { kd[j] = v[j] * __expf(-b4[j]); ke[j] = v[j] * __expf(bl[j] - b4[j]); }
;                 tile_put4(rl, pcl, pk4(kd));
	v_sub_f32_e32 v175, v153, v215
	v_sub_f32_e32 v204, v154, v216
	v_sub_f32_e32 v205, v155, v217
	v_mul_f32_e32 v214, 0xbfb8aa3b, v214
	v_mul_f32_e32 v215, 0xbfb8aa3b, v215
	v_mul_f32_e32 v216, 0xbfb8aa3b, v216
	v_mul_f32_e32 v217, 0xbfb8aa3b, v217
	v_mul_f32_e32 v174, 0x3fb8aa3b, v174
	v_mul_f32_e32 v175, 0x3fb8aa3b, v175
	v_mul_f32_e32 v204, 0x3fb8aa3b, v204
	v_mul_f32_e32 v205, 0x3fb8aa3b, v205
	v_exp_f32_e32 v214, v214
	v_exp_f32_e32 v215, v215
	v_exp_f32_e32 v216, v216
	v_exp_f32_e32 v217, v217
	v_exp_f32_e32 v174, v174
	v_exp_f32_e32 v175, v175
	v_exp_f32_e32 v204, v204
	v_exp_f32_e32 v205, v205
	v_pk_mul_f32 v[214:215], v[36:37], v[214:215]
	v_pk_mul_f32 v[216:217], v[38:39], v[216:217]
	v_pk_mul_f32 v[36:37], v[36:37], v[174:175]
	v_pk_mul_f32 v[38:39], v[38:39], v[204:205]
	v_cvt_pk_bf16_f32 v214, v214, v215
	v_cvt_pk_bf16_f32 v215, v216, v217
	ds_write_b64 v162, v[214:215] offset:8192
	v_sub_f32_e32 v174, v156, v224
	v_sub_f32_e32 v175, v157, v225
	v_sub_f32_e32 v204, v158, v226
	v_sub_f32_e32 v205, v159, v227
	v_mul_f32_e32 v224, 0xbfb8aa3b, v224
	v_mul_f32_e32 v225, 0xbfb8aa3b, v225
	v_mul_f32_e32 v226, 0xbfb8aa3b, v226
	v_mul_f32_e32 v227, 0xbfb8aa3b, v227
	v_mul_f32_e32 v174, 0x3fb8aa3b, v174
	v_mul_f32_e32 v175, 0x3fb8aa3b, v175
	v_mul_f32_e32 v204, 0x3fb8aa3b, v204
	v_mul_f32_e32 v205, 0x3fb8aa3b, v205
	v_exp_f32_e32 v224, v224
	v_exp_f32_e32 v225, v225
	v_exp_f32_e32 v226, v226
	v_exp_f32_e32 v227, v227
	v_exp_f32_e32 v174, v174
	v_exp_f32_e32 v175, v175
	v_exp_f32_e32 v204, v204
	v_exp_f32_e32 v205, v205
	v_pk_mul_f32 v[224:225], v[32:33], v[224:225]
	v_pk_mul_f32 v[226:227], v[34:35], v[226:227]
	v_pk_mul_f32 v[32:33], v[32:33], v[174:175]
	v_pk_mul_f32 v[34:35], v[34:35], v[204:205]
	v_cvt_pk_bf16_f32 v224, v224, v225
	v_cvt_pk_bf16_f32 v225, v226, v227
	ds_write_b64 v163, v[224:225] offset:8192
	v_sub_f32_e32 v174, v144, v228
	v_sub_f32_e32 v175, v145, v229
	v_sub_f32_e32 v204, v146, v230
	v_sub_f32_e32 v205, v147, v231
	v_mul_f32_e32 v228, 0xbfb8aa3b, v228
	v_mul_f32_e32 v229, 0xbfb8aa3b, v229
	v_mul_f32_e32 v230, 0xbfb8aa3b, v230
	v_mul_f32_e32 v231, 0xbfb8aa3b, v231
	v_mul_f32_e32 v174, 0x3fb8aa3b, v174
	v_mul_f32_e32 v175, 0x3fb8aa3b, v175
	v_mul_f32_e32 v204, 0x3fb8aa3b, v204
	v_mul_f32_e32 v205, 0x3fb8aa3b, v205
	v_exp_f32_e32 v228, v228
	v_exp_f32_e32 v229, v229
	v_exp_f32_e32 v230, v230
	v_exp_f32_e32 v231, v231
	v_exp_f32_e32 v174, v174
	v_exp_f32_e32 v175, v175
	v_exp_f32_e32 v204, v204
	v_exp_f32_e32 v205, v205
	v_pk_mul_f32 v[228:229], v[28:29], v[228:229]
	v_pk_mul_f32 v[230:231], v[30:31], v[230:231]
	v_pk_mul_f32 v[28:29], v[28:29], v[174:175]
	v_pk_mul_f32 v[30:31], v[30:31], v[204:205]
	v_cvt_pk_bf16_f32 v228, v228, v229
	v_cvt_pk_bf16_f32 v229, v230, v231
	ds_write_b64 v162, v[228:229] offset:16384
	v_sub_f32_e32 v174, v148, v232
	v_sub_f32_e32 v175, v149, v233
	v_sub_f32_e32 v204, v150, v234
	v_sub_f32_e32 v205, v151, v235
	v_mul_f32_e32 v232, 0xbfb8aa3b, v232
	v_mul_f32_e32 v233, 0xbfb8aa3b, v233
	v_mul_f32_e32 v234, 0xbfb8aa3b, v234
	v_mul_f32_e32 v235, 0xbfb8aa3b, v235
	v_mul_f32_e32 v174, 0x3fb8aa3b, v174
	v_mul_f32_e32 v175, 0x3fb8aa3b, v175
	v_mul_f32_e32 v204, 0x3fb8aa3b, v204
	v_mul_f32_e32 v205, 0x3fb8aa3b, v205
	v_exp_f32_e32 v232, v232
	v_exp_f32_e32 v233, v233
	v_exp_f32_e32 v234, v234
	v_exp_f32_e32 v235, v235
	v_exp_f32_e32 v174, v174
	v_exp_f32_e32 v175, v175
	v_exp_f32_e32 v204, v204
	v_exp_f32_e32 v205, v205
	v_pk_mul_f32 v[232:233], v[24:25], v[232:233]
	v_pk_mul_f32 v[234:235], v[26:27], v[234:235]
	v_pk_mul_f32 v[24:25], v[24:25], v[174:175]
	v_pk_mul_f32 v[26:27], v[26:27], v[204:205]
	v_cvt_pk_bf16_f32 v232, v232, v233
	v_cvt_pk_bf16_f32 v233, v234, v235
	ds_write_b64 v163, v[232:233] offset:16384
	v_sub_f32_e32 v174, v152, v236
	v_sub_f32_e32 v175, v153, v237
	v_sub_f32_e32 v204, v154, v238
	v_sub_f32_e32 v205, v155, v239
	v_mul_f32_e32 v236, 0xbfb8aa3b, v236
	v_mul_f32_e32 v237, 0xbfb8aa3b, v237
	v_mul_f32_e32 v238, 0xbfb8aa3b, v238
	v_mul_f32_e32 v239, 0xbfb8aa3b, v239
	v_mul_f32_e32 v174, 0x3fb8aa3b, v174
	v_mul_f32_e32 v175, 0x3fb8aa3b, v175
	v_mul_f32_e32 v204, 0x3fb8aa3b, v204
	v_mul_f32_e32 v205, 0x3fb8aa3b, v205
	v_exp_f32_e32 v236, v236
	v_exp_f32_e32 v237, v237
	v_exp_f32_e32 v238, v238
	v_exp_f32_e32 v239, v239
	v_exp_f32_e32 v174, v174
	v_exp_f32_e32 v175, v175
	v_exp_f32_e32 v204, v204
	v_exp_f32_e32 v205, v205
	v_pk_mul_f32 v[236:237], v[20:21], v[236:237]
	v_pk_mul_f32 v[238:239], v[22:23], v[238:239]
	v_pk_mul_f32 v[20:21], v[20:21], v[174:175]
	v_pk_mul_f32 v[22:23], v[22:23], v[204:205]
	v_cvt_pk_bf16_f32 v236, v236, v237
	v_cvt_pk_bf16_f32 v237, v238, v239
	ds_write_b64 v162, v[236:237] offset:16640
	v_sub_f32_e32 v174, v156, v240
	v_sub_f32_e32 v175, v157, v241
	v_sub_f32_e32 v204, v158, v242
	v_sub_f32_e32 v205, v159, v243
	v_mul_f32_e32 v240, 0xbfb8aa3b, v240
	v_mul_f32_e32 v241, 0xbfb8aa3b, v241
	v_mul_f32_e32 v242, 0xbfb8aa3b, v242
	v_mul_f32_e32 v243, 0xbfb8aa3b, v243
	v_mul_f32_e32 v174, 0x3fb8aa3b, v174
	v_mul_f32_e32 v175, 0x3fb8aa3b, v175
	v_mul_f32_e32 v204, 0x3fb8aa3b, v204
	v_mul_f32_e32 v205, 0x3fb8aa3b, v205
	v_exp_f32_e32 v240, v240
	v_exp_f32_e32 v241, v241
	v_exp_f32_e32 v242, v242
	v_exp_f32_e32 v243, v243
	v_exp_f32_e32 v174, v174
	v_exp_f32_e32 v175, v175
	v_exp_f32_e32 v204, v204
	v_exp_f32_e32 v205, v205
	v_pk_mul_f32 v[240:241], v[16:17], v[240:241]
	v_pk_mul_f32 v[242:243], v[18:19], v[242:243]
	v_pk_mul_f32 v[16:17], v[16:17], v[174:175]
	v_pk_mul_f32 v[18:19], v[18:19], v[204:205]
	v_cvt_pk_bf16_f32 v240, v240, v241
	v_cvt_pk_bf16_f32 v241, v242, v243
	ds_write_b64 v163, v[240:241] offset:16640
	v_sub_f32_e32 v174, v144, v244
; DEV u32x2 pk4(f32x4 v) { u32x2 r = {pk_bf16(v[0], v[1]), pk_bf16(v[2], v[3])}; return r; }
; DEV int sig4(int x) { return ((x & 1) << 1) | (x >> 1); }
;   DEV void operator()(f32x4 (&acc)[2][2][4][2], int brow, int bcol, int wr, int wc, int fr, int fq) const {
;     ...
;               const f32x4 b4 = *(const f32x4*)(bmat + (size_t)tok * 1024 + lc);
;               const int pcl = (cl & ~15) + 4 * sig4((cl >> 2) & 3);
;               if (mode == 3) {
;                 for (int j = 0; j < 4; ++j) v[j] = v[j] * scale * __expf(b4[j]);
;                 tile_put4(rl, pcl, pk4(v));
;               } else {
;                 const f32x4 bl = *(const f32x4*)(bmat + (size_t)(tok | 63) * 1024 + lc);
;                 f32x4 kd, ke;
;                 for (int j = 0; j < 4; ++j) { kd[j] = v[j] * __expf(-b4[j]); ke[j] = v[j] * __expf(bl[j] - b4[j]); }
;                 tile_put4(rl, pcl, pk4(kd));
;                 (void)ke;
;               }
;             }
;           }
;       }
;     __syncthreads();
;     tile_rows_out<true>(out + (size_t)brow * ld + (bcol - segstart), (size_t)ld, (wr * 4 + wc) * 64 + fq * 16 + fr);
	v_sub_f32_e32 v175, v145, v245
	v_sub_f32_e32 v204, v146, v246
	v_sub_f32_e32 v205, v147, v247
	v_mul_f32_e32 v244, 0xbfb8aa3b, v244
	v_mul_f32_e32 v245, 0xbfb8aa3b, v245
	v_mul_f32_e32 v246, 0xbfb8aa3b, v246
	v_mul_f32_e32 v247, 0xbfb8aa3b, v247
	v_mul_f32_e32 v174, 0x3fb8aa3b, v174
	v_mul_f32_e32 v175, 0x3fb8aa3b, v175
	v_mul_f32_e32 v204, 0x3fb8aa3b, v204
	v_mul_f32_e32 v205, 0x3fb8aa3b, v205
	v_exp_f32_e32 v244, v244
	v_exp_f32_e32 v245, v245
	v_exp_f32_e32 v246, v246
	v_exp_f32_e32 v247, v247
	v_exp_f32_e32 v174, v174
	v_exp_f32_e32 v175, v175
	v_exp_f32_e32 v204, v204
	v_exp_f32_e32 v205, v205
	v_pk_mul_f32 v[244:245], v[12:13], v[244:245]
	v_pk_mul_f32 v[246:247], v[14:15], v[246:247]
	v_pk_mul_f32 v[12:13], v[12:13], v[174:175]
	v_pk_mul_f32 v[14:15], v[14:15], v[204:205]
	v_cvt_pk_bf16_f32 v244, v244, v245
	v_cvt_pk_bf16_f32 v245, v246, v247
	ds_write_b64 v162, v[244:245] offset:24832
	v_sub_f32_e32 v174, v148, v248
	v_sub_f32_e32 v175, v149, v249
	v_sub_f32_e32 v204, v150, v250
	v_sub_f32_e32 v205, v151, v251
	v_mul_f32_e32 v248, 0xbfb8aa3b, v248
	v_mul_f32_e32 v249, 0xbfb8aa3b, v249
	v_mul_f32_e32 v250, 0xbfb8aa3b, v250
	v_mul_f32_e32 v251, 0xbfb8aa3b, v251
	v_mul_f32_e32 v174, 0x3fb8aa3b, v174
	v_mul_f32_e32 v175, 0x3fb8aa3b, v175
	v_mul_f32_e32 v204, 0x3fb8aa3b, v204
	v_mul_f32_e32 v205, 0x3fb8aa3b, v205
	v_exp_f32_e32 v248, v248
	v_exp_f32_e32 v249, v249
	v_exp_f32_e32 v250, v250
	v_exp_f32_e32 v251, v251
	v_exp_f32_e32 v174, v174
	v_exp_f32_e32 v175, v175
	v_exp_f32_e32 v204, v204
	v_exp_f32_e32 v205, v205
	v_pk_mul_f32 v[248:249], v[8:9], v[248:249]
	v_pk_mul_f32 v[250:251], v[10:11], v[250:251]
	v_pk_mul_f32 v[8:9], v[8:9], v[174:175]
	v_pk_mul_f32 v[10:11], v[10:11], v[204:205]
	v_cvt_pk_bf16_f32 v248, v248, v249
	v_cvt_pk_bf16_f32 v249, v250, v251
	ds_write_b64 v163, v[248:249] offset:24832
	v_sub_f32_e32 v174, v152, v166
	v_sub_f32_e32 v175, v153, v167
	v_sub_f32_e32 v204, v154, v168
	v_sub_f32_e32 v205, v155, v169
	v_mul_f32_e32 v166, 0xbfb8aa3b, v166
	v_mul_f32_e32 v167, 0xbfb8aa3b, v167
	v_mul_f32_e32 v168, 0xbfb8aa3b, v168
	v_mul_f32_e32 v169, 0xbfb8aa3b, v169
	v_mul_f32_e32 v174, 0x3fb8aa3b, v174
	v_mul_f32_e32 v175, 0x3fb8aa3b, v175
	v_mul_f32_e32 v204, 0x3fb8aa3b, v204
	v_mul_f32_e32 v205, 0x3fb8aa3b, v205
	v_exp_f32_e32 v166, v166
	v_exp_f32_e32 v167, v167
	v_exp_f32_e32 v168, v168
	v_exp_f32_e32 v169, v169
	v_exp_f32_e32 v174, v174
	v_exp_f32_e32 v175, v175
	v_exp_f32_e32 v204, v204
	v_exp_f32_e32 v205, v205
	v_pk_mul_f32 v[166:167], v[4:5], v[166:167]
	v_pk_mul_f32 v[168:169], v[6:7], v[168:169]
	v_pk_mul_f32 v[4:5], v[4:5], v[174:175]
	v_pk_mul_f32 v[6:7], v[6:7], v[204:205]
	v_cvt_pk_bf16_f32 v166, v166, v167
	v_cvt_pk_bf16_f32 v167, v168, v169
	ds_write_b64 v162, v[166:167] offset:24576
	v_sub_f32_e32 v174, v156, v170
	v_sub_f32_e32 v175, v157, v171
	v_sub_f32_e32 v204, v158, v172
	v_sub_f32_e32 v205, v159, v173
	v_mul_f32_e32 v170, 0xbfb8aa3b, v170
	v_mul_f32_e32 v171, 0xbfb8aa3b, v171
	v_mul_f32_e32 v172, 0xbfb8aa3b, v172
	v_mul_f32_e32 v173, 0xbfb8aa3b, v173
	v_mul_f32_e32 v174, 0x3fb8aa3b, v174
	v_mul_f32_e32 v175, 0x3fb8aa3b, v175
	v_mul_f32_e32 v204, 0x3fb8aa3b, v204
	v_mul_f32_e32 v205, 0x3fb8aa3b, v205
	v_exp_f32_e32 v170, v170
	v_exp_f32_e32 v171, v171
	v_exp_f32_e32 v172, v172
	v_exp_f32_e32 v173, v173
	v_exp_f32_e32 v174, v174
	v_exp_f32_e32 v175, v175
	v_exp_f32_e32 v204, v204
	v_exp_f32_e32 v205, v205
	v_pk_mul_f32 v[170:171], v[0:1], v[170:171]
	v_pk_mul_f32 v[172:173], v[2:3], v[172:173]
	v_pk_mul_f32 v[0:1], v[0:1], v[174:175]
	v_pk_mul_f32 v[2:3], v[2:3], v[204:205]
	v_cvt_pk_bf16_f32 v170, v170, v171
	v_cvt_pk_bf16_f32 v171, v172, v173
	ds_write_b64 v163, v[170:171] offset:24576
	s_mul_i32 s0, s4, s8
	s_sub_i32 s1, s6, s36
	s_add_i32 s0, s0, s1
	s_ashr_i32 s1, s0, 31
	s_lshl_b64 s[0:1], s[0:1], 1
	s_add_u32 s0, s14, s0
	s_addc_u32 s1, s15, s1
	v_lshrrev_b32_e32 v138, 5, v198
	v_and_b32_e32 v139, 31, v198
	v_xor_b32_e32 v139, v139, v138
	v_mul_lo_u32 v140, v138, s8
	v_lshlrev_b32_e32 v140, 1, v140
	v_lshl_add_u32 v141, v139, 4, v140
	v_xor_b32_e32 v139, 16, v139
	v_lshl_add_u32 v142, v139, 4, v140
	s_lshl_b32 s5, s8, 5
	v_add_u32_e32 v142, s5, v142
	s_lshl_b32 s5, s8, 6
	v_lshlrev_b32_e32 v143, 4, v198
	v_add_u32_e32 v144, 0x10000, v143
	s_waitcnt lgkmcnt(0)
	s_barrier
; DEV u32x2 pk4(f32x4 v) { u32x2 r = {pk_bf16(v[0], v[1]), pk_bf16(v[2], v[3])}; return r; }
; template <bool NT = false>
; DEV void tile_rows_out(bf16_t* __restrict__ out0, const size_t ld, const int tid) {
; #pragma unroll
;   for (int i = 0; i < 16; ++i) {
;     const int id = i * 512 + tid, r = id >> 5, pos = id & 31, c = pos ^ (r & 31);
;     const u32x4 v = *(const u32x4*)(smem + r * 512 + pos * 16);
;     if (NT) __builtin_nontemporal_store(v, (u32x4*)(out0 + (size_t)r * ld + 8 * c)); else *(u32x4*)(out0 + (size_t)r * ld + 8 * c) = v;
;   }
;   DEV void operator()(f32x4 (&acc)[2][2][4][2], int brow, int bcol, int wr, int wc, int fr, int fq) const {
;     ...
;       for (int ai = 0; ai < 2; ++ai)
; #pragma unroll
;         for (int m = 0; m < 4; ++m) {
;           const int rl = ai * 128 + wr * 64 + m * 16 + fr, tok = brow + rl;
;           const int tposl = (rl & ~15) + sig16(rl & 15);
; #pragma unroll
;           for (int bj = 0; bj < 2; ++bj)
; #pragma unroll
;             for (int n = 0; n < 2; ++n) {
;               const int cl = bj * 128 + wc * 32 + n * 16 + fq * 4, lc = bcol - segstart + cl;
;               const f32x4 v = acc[ai][bj][m][n];
;               const f32x4 b4 = *(const f32x4*)(bmat + (size_t)tok * 1024 + lc);
;               const f32x4 bl = *(const f32x4*)(bmat + (size_t)(tok | 63) * 1024 + lc);
;               const u32x2 kk = pk4((f32x4){v[0] * __expf(bl[0] - b4[0]), v[1] * __expf(bl[1] - b4[1]), v[2] * __expf(bl[2] - b4[2]), v[3] * __expf(bl[3] - b4[3])});
; #pragma unroll
;               for (int j = 0; j < 4; ++j) {
;                 const int row = cl + j;
;                 const unsigned short val = (unsigned short)((j & 1) ? (kk[j >> 1] >> 16) : (kk[j >> 1] & 0xffff));
;                 *(unsigned short*)(smem + row * 512 + (((tposl >> 3) ^ (row & 31)) * 16) + (tposl & 7) * 2) = val;
;               }
	ds_read_b128 v[180:183], v143
	ds_read_b128 v[184:187], v143 offset:8192
	ds_read_b128 v[188:191], v143 offset:16384
	ds_read_b128 v[192:195], v143 offset:24576
	ds_read_b128 v[206:209], v143 offset:32768
	ds_read_b128 v[210:213], v143 offset:40960
	ds_read_b128 v[214:217], v143 offset:49152
	ds_read_b128 v[224:227], v143 offset:57344
	ds_read_b128 v[228:231], v144
	ds_read_b128 v[232:235], v144 offset:8192
	ds_read_b128 v[236:239], v144 offset:16384
	ds_read_b128 v[240:243], v144 offset:24576
	ds_read_b128 v[244:247], v144 offset:32768
	ds_read_b128 v[248:251], v144 offset:40960
	ds_read_b128 v[166:169], v144 offset:49152
	ds_read_b128 v[170:173], v144 offset:57344
	s_waitcnt lgkmcnt(15)
	global_store_dwordx4 v141, v[180:183], s[0:1] nt
	v_add_u32_e32 v141, s5, v141
	s_waitcnt lgkmcnt(14)
	global_store_dwordx4 v142, v[184:187], s[0:1] nt
	v_add_u32_e32 v142, s5, v142
	s_waitcnt lgkmcnt(13)
	global_store_dwordx4 v141, v[188:191], s[0:1] nt
	v_add_u32_e32 v141, s5, v141
	s_waitcnt lgkmcnt(12)
	global_store_dwordx4 v142, v[192:195], s[0:1] nt
	v_add_u32_e32 v142, s5, v142
	s_waitcnt lgkmcnt(11)
	global_store_dwordx4 v141, v[206:209], s[0:1] nt
	v_add_u32_e32 v141, s5, v141
	s_waitcnt lgkmcnt(10)
	global_store_dwordx4 v142, v[210:213], s[0:1] nt
	v_add_u32_e32 v142, s5, v142
	s_waitcnt lgkmcnt(9)
	global_store_dwordx4 v141, v[214:217], s[0:1] nt
	v_add_u32_e32 v141, s5, v141
	s_waitcnt lgkmcnt(8)
	global_store_dwordx4 v142, v[224:227], s[0:1] nt
	v_add_u32_e32 v142, s5, v142
	s_waitcnt lgkmcnt(7)
	global_store_dwordx4 v141, v[228:231], s[0:1] nt
	v_add_u32_e32 v141, s5, v141
	s_waitcnt lgkmcnt(6)
	global_store_dwordx4 v142, v[232:235], s[0:1] nt
	v_add_u32_e32 v142, s5, v142
	s_waitcnt lgkmcnt(5)
	global_store_dwordx4 v141, v[236:239], s[0:1] nt
	v_add_u32_e32 v141, s5, v141
	s_waitcnt lgkmcnt(4)
	global_store_dwordx4 v142, v[240:243], s[0:1] nt
	v_add_u32_e32 v142, s5, v142
	s_waitcnt lgkmcnt(3)
	global_store_dwordx4 v141, v[244:247], s[0:1] nt
	v_add_u32_e32 v141, s5, v141
	s_waitcnt lgkmcnt(2)
	global_store_dwordx4 v142, v[248:251], s[0:1] nt
	v_add_u32_e32 v142, s5, v142
	s_waitcnt lgkmcnt(1)
	global_store_dwordx4 v141, v[166:169], s[0:1] nt
	s_waitcnt lgkmcnt(0)
	global_store_dwordx4 v142, v[170:173], s[0:1] nt
	v_and_b32_e32 v148, 15, v198
	v_bfe_u32 v149, v198, 4, 2
	v_bfe_u32 v150, v198, 6, 2
	v_lshrrev_b32_e32 v151, 8, v198
	v_bfe_u32 v152, v148, 2, 1
	v_lshl_or_b32 v152, v151, 3, v152
	v_lshlrev_b32_e32 v153, 2, v149
	v_xor_b32_e32 v152, v152, v153
	v_lshlrev_b32_e32 v154, 5, v150
	v_lshl_add_u32 v154, v149, 2, v154
	v_lshlrev_b32_e32 v154, 9, v154
	v_lshrrev_b32_e32 v155, 3, v148
	v_and_b32_e32 v156, 3, v148
	v_lshl_add_u32 v155, v155, 2, v156
	v_lshl_add_u32 v154, v155, 1, v154
	v_xor_b32_e32 v157, 0, v152
	v_lshl_add_u32 v128, v157, 4, v154
	v_add_u32_e32 v136, 0x10000, v128
	v_xor_b32_e32 v157, 1, v152
	v_lshl_add_u32 v129, v157, 4, v154
	v_add_u32_e32 v137, 0x10000, v129
	v_xor_b32_e32 v157, 2, v152
	v_lshl_add_u32 v130, v157, 4, v154
	v_add_u32_e32 v138, 0x10000, v130
	v_xor_b32_e32 v157, 3, v152
	v_lshl_add_u32 v131, v157, 4, v154
	v_add_u32_e32 v139, 0x10000, v131
	v_xor_b32_e32 v157, 4, v152
	v_lshl_add_u32 v132, v157, 4, v154
	v_add_u32_e32 v140, 0x10000, v132
	v_xor_b32_e32 v157, 5, v152
	v_lshl_add_u32 v133, v157, 4, v154
	v_add_u32_e32 v141, 0x10000, v133
	v_xor_b32_e32 v157, 6, v152
	v_lshl_add_u32 v134, v157, 4, v154
	v_add_u32_e32 v142, 0x10000, v134
	v_xor_b32_e32 v157, 7, v152
	v_lshl_add_u32 v135, v157, 4, v154
	v_add_u32_e32 v143, 0x10000, v135
	s_waitcnt lgkmcnt(0)
	s_barrier
	v_cvt_pk_bf16_f32 v124, v124, v125
	v_cvt_pk_bf16_f32 v125, v126, v127
	ds_write_b16 v128, v124
	ds_write_b16_d16_hi v129, v124 offset:512
	ds_write_b16 v130, v125 offset:1024
	ds_write_b16_d16_hi v131, v125 offset:1536
	v_cvt_pk_bf16_f32 v120, v120, v121
	v_cvt_pk_bf16_f32 v121, v122, v123
	ds_write_b16 v128, v120 offset:8448
	ds_write_b16_d16_hi v129, v120 offset:8960
	ds_write_b16 v130, v121 offset:9472
	ds_write_b16_d16_hi v131, v121 offset:9984
	v_cvt_pk_bf16_f32 v116, v116, v117
	v_cvt_pk_bf16_f32 v117, v118, v119
	ds_write_b16 v136, v116
	ds_write_b16_d16_hi v137, v116 offset:512
	ds_write_b16 v138, v117 offset:1024
	ds_write_b16_d16_hi v139, v117 offset:1536
	v_cvt_pk_bf16_f32 v112, v112, v113
	v_cvt_pk_bf16_f32 v113, v114, v115
	ds_write_b16 v136, v112 offset:8448
	ds_write_b16_d16_hi v137, v112 offset:8960
	ds_write_b16 v138, v113 offset:9472
	ds_write_b16_d16_hi v139, v113 offset:9984
	v_cvt_pk_bf16_f32 v108, v108, v109
	v_cvt_pk_bf16_f32 v109, v110, v111
	ds_write_b16 v130, v108
	ds_write_b16_d16_hi v131, v108 offset:512
	ds_write_b16 v128, v109 offset:1024
	ds_write_b16_d16_hi v129, v109 offset:1536
	v_cvt_pk_bf16_f32 v104, v104, v105
	v_cvt_pk_bf16_f32 v105, v106, v107
	ds_write_b16 v130, v104 offset:8448
	ds_write_b16_d16_hi v131, v104 offset:8960
	ds_write_b16 v128, v105 offset:9472
	ds_write_b16_d16_hi v129, v105 offset:9984
	v_cvt_pk_bf16_f32 v100, v100, v101
	v_cvt_pk_bf16_f32 v101, v102, v103
	ds_write_b16 v138, v100
	ds_write_b16_d16_hi v139, v100 offset:512
	ds_write_b16 v136, v101 offset:1024
	ds_write_b16_d16_hi v137, v101 offset:1536
	v_cvt_pk_bf16_f32 v96, v96, v97
	v_cvt_pk_bf16_f32 v97, v98, v99
	ds_write_b16 v138, v96 offset:8448
	ds_write_b16_d16_hi v139, v96 offset:8960
	ds_write_b16 v136, v97 offset:9472
	ds_write_b16_d16_hi v137, v97 offset:9984
	v_cvt_pk_bf16_f32 v92, v92, v93
	v_cvt_pk_bf16_f32 v93, v94, v95
	ds_write_b16 v132, v92
	ds_write_b16_d16_hi v133, v92 offset:512
	ds_write_b16 v134, v93 offset:1024
	ds_write_b16_d16_hi v135, v93 offset:1536
	v_cvt_pk_bf16_f32 v88, v88, v89
; DEV u32x2 pk4(f32x4 v) { u32x2 r = {pk_bf16(v[0], v[1]), pk_bf16(v[2], v[3])}; return r; }
; template <bool NT = false>
; DEV void tile_rows_out(bf16_t* __restrict__ out0, const size_t ld, const int tid) {
; #pragma unroll
;   for (int i = 0; i < 16; ++i) {
;     const int id = i * 512 + tid, r = id >> 5, pos = id & 31, c = pos ^ (r & 31);
;     const u32x4 v = *(const u32x4*)(smem + r * 512 + pos * 16);
;   DEV void operator()(f32x4 (&acc)[2][2][4][2], int brow, int bcol, int wr, int wc, int fr, int fq) const {
;     ...
;               const u32x2 kk = pk4((f32x4){v[0] * __expf(bl[0] - b4[0]), v[1] * __expf(bl[1] - b4[1]), v[2] * __expf(bl[2] - b4[2]), v[3] * __expf(bl[3] - b4[3])});
; #pragma unroll
;               for (int j = 0; j < 4; ++j) {
;                 const int row = cl + j;
;                 const unsigned short val = (unsigned short)((j & 1) ? (kk[j >> 1] >> 16) : (kk[j >> 1] & 0xffff));
;                 *(unsigned short*)(smem + row * 512 + (((tposl >> 3) ^ (row & 31)) * 16) + (tposl & 7) * 2) = val;
;               }
;             }
;         }
;       __syncthreads();
;       const int bt = brow >> 11, tl0 = brow & 2047, hd = (bcol - segstart) >> 8;
;       tile_rows_out<true>(keT + ((size_t)((bt * 4 + hd) * 256)) * 2048 + tl0, 2048, (wr * 4 + wc) * 64 + fq * 16 + fr);
	v_cvt_pk_bf16_f32 v89, v90, v91
	ds_write_b16 v132, v88 offset:8448
	ds_write_b16_d16_hi v133, v88 offset:8960
	ds_write_b16 v134, v89 offset:9472
	ds_write_b16_d16_hi v135, v89 offset:9984
	v_cvt_pk_bf16_f32 v84, v84, v85
	v_cvt_pk_bf16_f32 v85, v86, v87
	ds_write_b16 v140, v84
	ds_write_b16_d16_hi v141, v84 offset:512
	ds_write_b16 v142, v85 offset:1024
	ds_write_b16_d16_hi v143, v85 offset:1536
	v_cvt_pk_bf16_f32 v80, v80, v81
	v_cvt_pk_bf16_f32 v81, v82, v83
	ds_write_b16 v140, v80 offset:8448
	ds_write_b16_d16_hi v141, v80 offset:8960
	ds_write_b16 v142, v81 offset:9472
	ds_write_b16_d16_hi v143, v81 offset:9984
	v_cvt_pk_bf16_f32 v76, v76, v77
	v_cvt_pk_bf16_f32 v77, v78, v79
	ds_write_b16 v134, v76
	ds_write_b16_d16_hi v135, v76 offset:512
	ds_write_b16 v132, v77 offset:1024
	ds_write_b16_d16_hi v133, v77 offset:1536
	v_cvt_pk_bf16_f32 v72, v72, v73
	v_cvt_pk_bf16_f32 v73, v74, v75
	ds_write_b16 v134, v72 offset:8448
	ds_write_b16_d16_hi v135, v72 offset:8960
	ds_write_b16 v132, v73 offset:9472
	ds_write_b16_d16_hi v133, v73 offset:9984
	v_cvt_pk_bf16_f32 v68, v68, v69
	v_cvt_pk_bf16_f32 v69, v70, v71
	ds_write_b16 v142, v68
	ds_write_b16_d16_hi v143, v68 offset:512
	ds_write_b16 v140, v69 offset:1024
	ds_write_b16_d16_hi v141, v69 offset:1536
	v_cvt_pk_bf16_f32 v64, v64, v65
	v_cvt_pk_bf16_f32 v65, v66, v67
	ds_write_b16 v142, v64 offset:8448
	ds_write_b16_d16_hi v143, v64 offset:8960
	ds_write_b16 v140, v65 offset:9472
	ds_write_b16_d16_hi v141, v65 offset:9984
	v_cvt_pk_bf16_f32 v60, v60, v61
	v_cvt_pk_bf16_f32 v61, v62, v63
	ds_write_b16 v128, v60 offset:256
	ds_write_b16_d16_hi v129, v60 offset:768
	ds_write_b16 v130, v61 offset:1280
	ds_write_b16_d16_hi v131, v61 offset:1792
	v_cvt_pk_bf16_f32 v56, v56, v57
	v_cvt_pk_bf16_f32 v57, v58, v59
	ds_write_b16 v128, v56 offset:8192
	ds_write_b16_d16_hi v129, v56 offset:8704
	ds_write_b16 v130, v57 offset:9216
	ds_write_b16_d16_hi v131, v57 offset:9728
	v_cvt_pk_bf16_f32 v52, v52, v53
	v_cvt_pk_bf16_f32 v53, v54, v55
	ds_write_b16 v136, v52 offset:256
	ds_write_b16_d16_hi v137, v52 offset:768
	ds_write_b16 v138, v53 offset:1280
	ds_write_b16_d16_hi v139, v53 offset:1792
	v_cvt_pk_bf16_f32 v48, v48, v49
	v_cvt_pk_bf16_f32 v49, v50, v51
	ds_write_b16 v136, v48 offset:8192
	ds_write_b16_d16_hi v137, v48 offset:8704
	ds_write_b16 v138, v49 offset:9216
	ds_write_b16_d16_hi v139, v49 offset:9728
	v_cvt_pk_bf16_f32 v44, v44, v45
	v_cvt_pk_bf16_f32 v45, v46, v47
	ds_write_b16 v130, v44 offset:256
	ds_write_b16_d16_hi v131, v44 offset:768
	ds_write_b16 v128, v45 offset:1280
	ds_write_b16_d16_hi v129, v45 offset:1792
	v_cvt_pk_bf16_f32 v40, v40, v41
	v_cvt_pk_bf16_f32 v41, v42, v43
	ds_write_b16 v130, v40 offset:8192
	ds_write_b16_d16_hi v131, v40 offset:8704
	ds_write_b16 v128, v41 offset:9216
	ds_write_b16_d16_hi v129, v41 offset:9728
	v_cvt_pk_bf16_f32 v36, v36, v37
	v_cvt_pk_bf16_f32 v37, v38, v39
	ds_write_b16 v138, v36 offset:256
	ds_write_b16_d16_hi v139, v36 offset:768
	ds_write_b16 v136, v37 offset:1280
	ds_write_b16_d16_hi v137, v37 offset:1792
	v_cvt_pk_bf16_f32 v32, v32, v33
	v_cvt_pk_bf16_f32 v33, v34, v35
	ds_write_b16 v138, v32 offset:8192
	ds_write_b16_d16_hi v139, v32 offset:8704
	ds_write_b16 v136, v33 offset:9216
	ds_write_b16_d16_hi v137, v33 offset:9728
	v_cvt_pk_bf16_f32 v28, v28, v29
	v_cvt_pk_bf16_f32 v29, v30, v31
	ds_write_b16 v132, v28 offset:256
	ds_write_b16_d16_hi v133, v28 offset:768
	ds_write_b16 v134, v29 offset:1280
	ds_write_b16_d16_hi v135, v29 offset:1792
	v_cvt_pk_bf16_f32 v24, v24, v25
	v_cvt_pk_bf16_f32 v25, v26, v27
	ds_write_b16 v132, v24 offset:8192
	ds_write_b16_d16_hi v133, v24 offset:8704
	ds_write_b16 v134, v25 offset:9216
	ds_write_b16_d16_hi v135, v25 offset:9728
	v_cvt_pk_bf16_f32 v20, v20, v21
	v_cvt_pk_bf16_f32 v21, v22, v23
	ds_write_b16 v140, v20 offset:256
	ds_write_b16_d16_hi v141, v20 offset:768
	ds_write_b16 v142, v21 offset:1280
	ds_write_b16_d16_hi v143, v21 offset:1792
	v_cvt_pk_bf16_f32 v16, v16, v17
	v_cvt_pk_bf16_f32 v17, v18, v19
	ds_write_b16 v140, v16 offset:8192
	ds_write_b16_d16_hi v141, v16 offset:8704
	ds_write_b16 v142, v17 offset:9216
	ds_write_b16_d16_hi v143, v17 offset:9728
	v_cvt_pk_bf16_f32 v12, v12, v13
	v_cvt_pk_bf16_f32 v13, v14, v15
	ds_write_b16 v134, v12 offset:256
	ds_write_b16_d16_hi v135, v12 offset:768
	ds_write_b16 v132, v13 offset:1280
	ds_write_b16_d16_hi v133, v13 offset:1792
	v_cvt_pk_bf16_f32 v8, v8, v9
	v_cvt_pk_bf16_f32 v9, v10, v11
	ds_write_b16 v134, v8 offset:8192
	ds_write_b16_d16_hi v135, v8 offset:8704
	ds_write_b16 v132, v9 offset:9216
	ds_write_b16_d16_hi v133, v9 offset:9728
	v_cvt_pk_bf16_f32 v4, v4, v5
	v_cvt_pk_bf16_f32 v5, v6, v7
	ds_write_b16 v142, v4 offset:256
	ds_write_b16_d16_hi v143, v4 offset:768
	ds_write_b16 v140, v5 offset:1280
	ds_write_b16_d16_hi v141, v5 offset:1792
	v_cvt_pk_bf16_f32 v0, v0, v1
	v_cvt_pk_bf16_f32 v1, v2, v3
	ds_write_b16 v142, v0 offset:8192
	ds_write_b16_d16_hi v143, v0 offset:8704
	ds_write_b16 v140, v1 offset:9216
	ds_write_b16_d16_hi v141, v1 offset:9728
	v_readlane_b32 s0, v253, 25
	v_readlane_b32 s1, v253, 26
	s_lshr_b32 s20, s4, 11
	s_lshl_b32 s20, s20, 2
	s_sub_i32 s21, s6, s36
	s_lshr_b32 s21, s21, 8
	s_add_i32 s20, s20, s21
	s_lshl_b32 s20, s20, 19
	s_and_b32 s21, s4, 0x7ff
	s_add_i32 s20, s20, s21
	s_lshl_b32 s20, s20, 1
	s_add_u32 s0, s0, s20
	s_addc_u32 s1, s1, 0
	v_lshrrev_b32_e32 v138, 5, v198
	v_and_b32_e32 v139, 31, v198
	v_xor_b32_e32 v139, v139, v138
	v_mul_u32_u24_e32 v140, 4096, v138
	v_lshl_add_u32 v141, v139, 4, v140
	v_xor_b32_e32 v139, 16, v139
	v_lshl_add_u32 v142, v139, 4, v140
	v_add_u32_e32 v142, 0x10000, v142
	s_mov_b32 s5, 0x20000
	v_lshlrev_b32_e32 v143, 4, v198
	v_add_u32_e32 v144, 0x10000, v143
	s_waitcnt lgkmcnt(0)
	s_barrier
	ds_read_b128 v[64:67], v143
	ds_read_b128 v[68:71], v143 offset:8192
	ds_read_b128 v[72:75], v143 offset:16384
	ds_read_b128 v[76:79], v143 offset:24576
	ds_read_b128 v[80:83], v143 offset:32768
	ds_read_b128 v[84:87], v143 offset:40960
	ds_read_b128 v[88:91], v143 offset:49152
	ds_read_b128 v[92:95], v143 offset:57344
	ds_read_b128 v[96:99], v144
	ds_read_b128 v[100:103], v144 offset:8192
	ds_read_b128 v[104:107], v144 offset:16384
	ds_read_b128 v[108:111], v144 offset:24576
	ds_read_b128 v[112:115], v144 offset:32768
	ds_read_b128 v[116:119], v144 offset:40960
	ds_read_b128 v[120:123], v144 offset:49152
	ds_read_b128 v[124:127], v144 offset:57344
	s_waitcnt lgkmcnt(0)
	v_mov_b32_e32 v62, v141
	v_mov_b32_e32 v63, v142
	s_mov_b32 s38, s0
	s_mov_b32 s39, s1
	s_mov_b32 s40, s5
	s_mov_b32 s41, 1
	s_branch .LBB0_1555
; DEV void phase1(const Params& p, const int base_item) {
;     ...
;     if (vt) gemm_tile<false>(a, w, 2048, brow, bcol, ev);
;     else gemm_tile<true>(a, w, 2048, brow, bcol, e);
;   }
.Lp1d_exit:
	s_cmp_eq_u32 s41, 0
	s_cbranch_scc1 .Lp1d_nost_x
	global_store_dwordx4 v62, v[64:67], s[38:39] nt
	v_add_u32_e32 v62, s40, v62
	global_store_dwordx4 v63, v[68:71], s[38:39] nt
	v_add_u32_e32 v63, s40, v63
	global_store_dwordx4 v62, v[72:75], s[38:39] nt
	v_add_u32_e32 v62, s40, v62
	global_store_dwordx4 v63, v[76:79], s[38:39] nt
	v_add_u32_e32 v63, s40, v63
	global_store_dwordx4 v62, v[80:83], s[38:39] nt
	v_add_u32_e32 v62, s40, v62
	global_store_dwordx4 v63, v[84:87], s[38:39] nt
	v_add_u32_e32 v63, s40, v63
	global_store_dwordx4 v62, v[88:91], s[38:39] nt
	v_add_u32_e32 v62, s40, v62
	global_store_dwordx4 v63, v[92:95], s[38:39] nt
	v_add_u32_e32 v63, s40, v63
	global_store_dwordx4 v62, v[96:99], s[38:39] nt
	v_add_u32_e32 v62, s40, v62
	global_store_dwordx4 v63, v[100:103], s[38:39] nt
	v_add_u32_e32 v63, s40, v63
	global_store_dwordx4 v62, v[104:107], s[38:39] nt
	v_add_u32_e32 v62, s40, v62
	global_store_dwordx4 v63, v[108:111], s[38:39] nt
	v_add_u32_e32 v63, s40, v63
	global_store_dwordx4 v62, v[112:115], s[38:39] nt
	v_add_u32_e32 v62, s40, v62
	global_store_dwordx4 v63, v[116:119], s[38:39] nt
	v_add_u32_e32 v63, s40, v63
	global_store_dwordx4 v62, v[120:123], s[38:39] nt
	global_store_dwordx4 v63, v[124:127], s[38:39] nt
.Lp1d_nost_x:
	s_mov_b32 s41, 0
	s_branch .LBB0_1258

; #define STAGE(P, BASE, br, kt) do { const char* _gb = (const char*)(BASE) + (((long)(br) * K + (long)(kt) * BK) << 1); \
;     __builtin_amdgcn_global_load_lds((const unsigned*)(_gb + so0), (unsigned*)((char*)(P) + tb), 16, 0, 0); \
;     __builtin_amdgcn_global_load_lds((const unsigned*)(_gb + so1), (unsigned*)((char*)(P) + tb + 8192), 16, 0, 0); } while (0)
; #define WAIT_V(n) asm volatile("s_waitcnt vmcnt(" #n ")" ::: "memory")
; #define BAR __builtin_amdgcn_s_barrier()
; template <bool SWAP, class Epi>
; DEV void gemm_tile(const bf16_t* __restrict__ A, const bf16_t* __restrict__ Bt, const int K, const int brow, const int bcol, const Epi& epi) {
;     ...
;   WAIT_V(0);
;   __syncthreads();
;   STAGE(SB(0, 0), Bt, bcol, 0); STAGE(SA(0, 0), A, brow, 0);
;   STAGE(SB(0, 1), Bt, bcol + HALF, 0); STAGE(SA(0, 1), A, brow + HALF, 0);
;   if (wr == 1) BAR;
;   WAIT_V(4); BAR;
;   STAGE(SB(1, 0), Bt, bcol, 1); STAGE(SA(1, 0), A, brow, 1); STAGE(SB(1, 1), Bt, bcol + HALF, 1);
.LBB0_2095:
	s_and_b64 vcc, exec, s[18:19]
	s_cbranch_vccz .LBB0_1555
	v_mov_b32_e32 v140, v179
	s_ashr_i32 s7, s6, 31
	v_ashrrev_i32_e32 v0, 31, v140
	v_lshrrev_b32_e32 v0, 26, v0
	v_add_u32_e32 v0, v140, v0
	v_ashrrev_i32_e32 v2, 6, v0
	v_bfe_i32 v0, v140, 27, 1
	v_lshlrev_b32_e32 v3, 4, v140
	v_lshrrev_b32_e32 v0, 22, v0
	v_add_u32_e32 v0, v3, v0
	v_and_b32_e32 v0, 0xfffffc00, v0
	v_sub_u32_e32 v0, v3, v0
	v_lshrrev_b32_e32 v1, 4, v0
	v_bitop3_b32 v1, v1, v0, 32 bitop3:0x6c
	v_ashrrev_i32_e32 v0, 31, v0
	v_lshrrev_b32_e32 v0, 26, v0
	v_lshlrev_b32_e32 v4, 3, v2
	v_add_u32_e32 v0, v1, v0
	v_and_b32_e32 v6, 0xffff0, v4
	v_ashrrev_i32_e32 v4, 6, v0
	v_mul_i32_i24_e32 v5, 64, v4
	v_sub_u32_e32 v1, v1, v5
	v_lshlrev_b32_e32 v0, 5, v2
	v_ashrrev_i16_sdwa v1, v218, sext(v1) dst_sel:DWORD dst_unused:UNUSED_PAD src0_sel:DWORD src1_sel:BYTE_0
	v_and_b32_e32 v0, 32, v0
	v_bfe_i32 v5, v1, 0, 16
	v_add_u32_e32 v0, v0, v5
	v_add_lshl_u32 v1, v4, v6, 12
	v_lshl_add_u32 v176, v0, 1, v1
	v_add_u32_e32 v0, 0x2000, v3
	v_ashrrev_i32_e32 v1, 31, v0
	v_lshrrev_b32_e32 v1, 22, v1
	v_add_u32_e32 v1, v0, v1
	v_ashrrev_i32_e32 v6, 10, v1
	v_mul_i32_i24_e32 v1, 0x400, v6
	s_lshl_b64 s[8:9], s[6:7], 12
	v_sub_u32_e32 v0, v0, v1
	s_add_u32 s12, s62, s8
	v_lshrrev_b32_e32 v1, 4, v0
	s_addc_u32 s13, s63, s9
	s_add_i32 s7, 0, 0x10000
	v_bitop3_b32 v0, v1, v0, 32 bitop3:0x6c
	v_add_u32_e32 v142, s7, v3
	v_ashrrev_i32_e32 v7, 31, v0
	v_readfirstlane_b32 s5, v142
	v_add_u32_e32 v143, 0x2000, v142
	v_lshrrev_b32_e32 v7, 26, v7
	s_mov_b32 m0, s5
	v_readfirstlane_b32 s5, v143
	v_add_u32_e32 v8, v0, v7
	s_waitcnt vmcnt(0)
	s_waitcnt lgkmcnt(0)
	s_barrier
	global_load_lds_dwordx4 v176, s[12:13]
	s_mov_b32 m0, s5
	s_ashr_i32 s5, s4, 31
	v_ashrrev_i32_e32 v7, 6, v8
	v_and_b32_e32 v8, 0xc0, v8
	s_lshl_b64 s[10:11], s[4:5], 12
	v_readlane_b32 s20, v253, 52
	v_sub_u32_e32 v0, v0, v8
	v_readlane_b32 s21, v253, 53
	s_add_u32 s14, s20, s10
	v_lshlrev_b32_e32 v1, 3, v6
	v_lshlrev_b32_e32 v9, 5, v6
	v_ashrrev_i16_sdwa v0, v218, sext(v0) dst_sel:DWORD dst_unused:UNUSED_PAD src0_sel:DWORD src1_sel:BYTE_0
	s_addc_u32 s15, s21, s11
	s_or_b32 s16, s6, 0x80
	v_and_b32_e32 v1, 0xffff0, v1
	v_and_b32_e32 v9, 32, v9
	v_bfe_i32 v8, v0, 0, 16
	s_ashr_i32 s17, s16, 31
	v_add_u32_e32 v0, v9, v8
	v_add_lshl_u32 v1, v7, v1, 12
	v_add_u32_e32 v144, 0, v3
	s_lshl_b64 s[16:17], s[16:17], 12
	v_lshl_add_u32 v0, v0, 1, v1
	v_readfirstlane_b32 s5, v144
	v_add_u32_e32 v145, 0x2000, v144
	s_add_u32 s16, s62, s16
	global_load_lds_dwordx4 v0, s[12:13]
	s_mov_b32 m0, s5
	v_readfirstlane_b32 s5, v145
	s_addc_u32 s17, s63, s17
	v_add_u32_e32 v146, s72, v3
	s_or_b32 s18, s4, 0x80
	global_load_lds_dwordx4 v176, s[14:15]
	s_mov_b32 m0, s5
	v_readfirstlane_b32 s5, v146
	v_add_u32_e32 v147, 0x2000, v146
	s_ashr_i32 s19, s18, 31
	global_load_lds_dwordx4 v0, s[14:15]
	s_mov_b32 m0, s5
	v_readfirstlane_b32 s5, v147
	s_lshl_b64 s[18:19], s[18:19], 12
	v_add_u32_e32 v148, 0x4000, v144
	global_load_lds_dwordx4 v176, s[16:17]
	s_mov_b32 m0, s5
	s_add_u32 s18, s20, s18
	v_readfirstlane_b32 s5, v148
	v_add_u32_e32 v149, 0x6000, v144
	global_load_lds_dwordx4 v0, s[16:17]
	s_addc_u32 s19, s21, s19
	s_mov_b32 m0, s5
	v_readfirstlane_b32 s5, v149
	global_load_lds_dwordx4 v176, s[18:19]
	s_mov_b32 m0, s5
	v_ashrrev_i32_e32 v9, 8, v140
	global_load_lds_dwordx4 v0, s[18:19]
	s_cmp_eq_u32 s41, 0
	s_cbranch_scc1 .Lp1d_nost_b
	global_store_dwordx4 v62, v[64:67], s[38:39] nt
	v_add_u32_e32 v62, s40, v62
	global_store_dwordx4 v63, v[68:71], s[38:39] nt
	v_add_u32_e32 v63, s40, v63
	global_store_dwordx4 v62, v[72:75], s[38:39] nt
	v_add_u32_e32 v62, s40, v62
	global_store_dwordx4 v63, v[76:79], s[38:39] nt
	v_add_u32_e32 v63, s40, v63
	global_store_dwordx4 v62, v[80:83], s[38:39] nt
	v_add_u32_e32 v62, s40, v62
	global_store_dwordx4 v63, v[84:87], s[38:39] nt
	v_add_u32_e32 v63, s40, v63
	global_store_dwordx4 v62, v[88:91], s[38:39] nt
	v_add_u32_e32 v62, s40, v62
	global_store_dwordx4 v63, v[92:95], s[38:39] nt
	v_add_u32_e32 v63, s40, v63
	global_store_dwordx4 v62, v[96:99], s[38:39] nt
	v_add_u32_e32 v62, s40, v62
	global_store_dwordx4 v63, v[100:103], s[38:39] nt
	v_add_u32_e32 v63, s40, v63
	global_store_dwordx4 v62, v[104:107], s[38:39] nt
	v_add_u32_e32 v62, s40, v62
	global_store_dwordx4 v63, v[108:111], s[38:39] nt
	v_add_u32_e32 v63, s40, v63
	global_store_dwordx4 v62, v[112:115], s[38:39] nt
	v_add_u32_e32 v62, s40, v62
	global_store_dwordx4 v63, v[116:119], s[38:39] nt
	v_add_u32_e32 v63, s40, v63
	global_store_dwordx4 v62, v[120:123], s[38:39] nt
	global_store_dwordx4 v63, v[124:127], s[38:39] nt
.Lp1d_nost_b:
	v_cmp_eq_u32_e32 vcc, 1, v9
	s_and_saveexec_b64 s[20:21], vcc
	s_cbranch_execz .LBB0_2098
	s_barrier
.LBB0_2098:
	s_or_b64 exec, exec, s[20:21]
	v_mov_b32_e32 v1, v177
	v_lshl_add_u64 v[12:13], s[12:13], 0, v[0:1]
	v_lshl_add_u64 v[16:17], s[14:15], 0, v[0:1]
	v_lshl_add_u64 v[20:21], s[16:17], 0, v[0:1]
	v_lshl_add_u64 v[128:129], s[18:19], 0, v[0:1]
	v_and_b32_e32 v0, 15, v140
	v_lshlrev_b32_e32 v23, 2, v140
	v_and_b32_e32 v1, 48, v140
	v_lshlrev_b32_e32 v0, 6, v0
	v_and_b32_e32 v23, 32, v23
	v_or_b32_e32 v22, v0, v1
	v_bitop3_b32 v0, v0, v23, v1 bitop3:0x36
	v_lshlrev_b32_e32 v1, 13, v9
	v_add_u32_e32 v151, s77, v3
	v_lshl_add_u64 v[10:11], s[12:13], 0, v[176:177]
	v_bitop3_b32 v9, v22, v1, v23 bitop3:0xde
	v_lshlrev_b32_e32 v1, 6, v140
	s_mov_b64 s[12:13], 0x80
	v_readfirstlane_b32 s5, v151
	v_add_u32_e32 v152, 0x2000, v151
	v_and_or_b32 v150, v1, s73, v0
	v_lshl_add_u64 v[0:1], v[10:11], 0, s[12:13]
	s_mov_b32 m0, s5
	v_readfirstlane_b32 s5, v152
	v_add_u32_e32 v153, 0x8000, v144
	v_lshl_add_u64 v[14:15], s[14:15], 0, v[176:177]
	s_cmp_eq_u32 s41, 0
	s_cbranch_scc1 .Lp1d_w4_b
	s_waitcnt vmcnt(20)
	s_branch .Lp1d_w4d_b

; #define STAGE(P, BASE, br, kt) do { const char* _gb = (const char*)(BASE) + (((long)(br) * K + (long)(kt) * BK) << 1); \
;     __builtin_amdgcn_global_load_lds((const unsigned*)(_gb + so0), (unsigned*)((char*)(P) + tb), 16, 0, 0); \
;     __builtin_amdgcn_global_load_lds((const unsigned*)(_gb + so1), (unsigned*)((char*)(P) + tb + 8192), 16, 0, 0); } while (0)
; #define WAIT_V(n) asm volatile("s_waitcnt vmcnt(" #n ")" ::: "memory")
; #define BAR __builtin_amdgcn_s_barrier()
; template <bool SWAP, class Epi>
; DEV void gemm_tile(const bf16_t* __restrict__ A, const bf16_t* __restrict__ Bt, const int K, const int brow, const int bcol, const Epi& epi) {
;     ...
;   WAIT_V(4); BAR;
;   STAGE(SB(1, 0), Bt, bcol, 1); STAGE(SA(1, 0), A, brow, 1); STAGE(SB(1, 1), Bt, bcol + HALF, 1);
;   WAIT_V(6); BAR;
.Lp1d_w4d_b:
	s_barrier
	global_load_lds_dwordx4 v[0:1], off
	v_lshl_add_u64 v[0:1], v[12:13], 0, s[12:13]
	s_mov_b32 m0, s5
	v_readfirstlane_b32 s5, v153
	v_add_u32_e32 v154, 0xa000, v144
	global_load_lds_dwordx4 v[0:1], off
	v_lshl_add_u64 v[0:1], v[14:15], 0, s[12:13]
	s_mov_b32 m0, s5
	v_readfirstlane_b32 s5, v154
	v_add_u32_e32 v155, s78, v3
	v_lshl_add_u64 v[18:19], s[16:17], 0, v[176:177]
	global_load_lds_dwordx4 v[0:1], off
	v_lshl_add_u64 v[0:1], v[16:17], 0, s[12:13]
	s_mov_b32 m0, s5
	v_readfirstlane_b32 s5, v155
	v_add_u32_e32 v156, 0x2000, v155
	global_load_lds_dwordx4 v[0:1], off
	v_lshl_add_u64 v[0:1], v[18:19], 0, s[12:13]
	s_mov_b32 m0, s5
	v_readfirstlane_b32 s5, v156
	global_load_lds_dwordx4 v[0:1], off
	v_lshl_add_u64 v[0:1], v[20:21], 0, s[12:13]
	s_mov_b32 m0, s5
	v_lshl_add_u64 v[130:131], s[18:19], 0, v[176:177]
	global_load_lds_dwordx4 v[0:1], off
	v_lshlrev_b32_e32 v0, 15, v2
	v_and_b32_e32 v0, 0xffff0000, v0
	v_lshl_add_u32 v0, v4, 12, v0
	v_and_b32_e32 v1, 1, v2
	v_lshl_or_b32 v0, v1, 6, v0
	v_lshl_add_u32 v176, v5, 1, v0
	v_lshlrev_b32_e32 v0, 15, v6
	v_and_b32_e32 v0, 0xffff0000, v0
	v_lshl_add_u32 v0, v7, 12, v0
	v_and_b32_e32 v1, 1, v6
	v_lshl_or_b32 v0, v1, 6, v0
	s_cmp_eq_u32 s41, 0
	s_cbranch_scc1 .Lp1d_w6_b
	s_waitcnt vmcnt(22)
	s_mov_b32 s41, 0
	s_branch .Lp1d_w6d_b

; #define STAGE(P, BASE, br, kt) do { const char* _gb = (const char*)(BASE) + (((long)(br) * K + (long)(kt) * BK) << 1); \
;     __builtin_amdgcn_global_load_lds((const unsigned*)(_gb + so0), (unsigned*)((char*)(P) + tb), 16, 0, 0); \
;     __builtin_amdgcn_global_load_lds((const unsigned*)(_gb + so1), (unsigned*)((char*)(P) + tb + 8192), 16, 0, 0); } while (0)
; #define WAIT_V(n) asm volatile("s_waitcnt vmcnt(" #n ")" ::: "memory")
; #define BAR __builtin_amdgcn_s_barrier()
; template <bool SWAP, class Epi>
; DEV void gemm_tile(const bf16_t* __restrict__ A, const bf16_t* __restrict__ Bt, const int K, const int brow, const int bcol, const Epi& epi) {
;     ...
;   f32x4 acc[2][2][4][2] = {};
;   bf16x8 At[4][2], B0[2][2], B1[2][2];
;   const int nt = K / BK;
;   const int tb = tidx * 16;
;   unsigned so0, so1;
;   { int r_, c_; stage_rc(tb, r_, c_); so0 = (unsigned)(r_ * K + c_) * 2u; stage_rc(tb + 8192, r_, c_); so1 = (unsigned)(r_ * K + c_) * 2u; }
;   const int tb16 = (fr * 64 + fq * 16) ^ ((fr >> 3) << 5);
;   const int a_rd = wr * 8192 + tb16, b_rd = wc * 4096 + tb16;
;   WAIT_V(0);
;   __syncthreads();
;   STAGE(SB(0, 0), Bt, bcol, 0); STAGE(SA(0, 0), A, brow, 0);
;   STAGE(SB(0, 1), Bt, bcol + HALF, 0); STAGE(SA(0, 1), A, brow + HALF, 0);
;   if (wr == 1) BAR;
;   WAIT_V(4); BAR;
;   STAGE(SB(1, 0), Bt, bcol, 1); STAGE(SA(1, 0), A, brow, 1); STAGE(SB(1, 1), Bt, bcol + HALF, 1);
;   WAIT_V(6); BAR;
.Lp1d_w6d_b:
	v_lshl_add_u32 v0, v8, 1, v0
	v_mov_b32_e32 v1, v177
	v_lshl_add_u64 v[134:135], s[10:11], 0, v[0:1]
	v_lshl_add_u64 v[138:139], s[8:9], 0, v[0:1]
	v_mov_b32_e32 v0, 0
	v_lshl_add_u64 v[132:133], s[10:11], 0, v[176:177]
	v_lshl_add_u64 v[136:137], s[8:9], 0, v[176:177]
	s_mov_b32 s5, -2
	v_add_u32_e32 v141, 0, v9
	s_mov_b64 s[8:9], s[62:63]
	v_mov_b32_e32 v1, v0
	v_mov_b32_e32 v2, v0
	v_mov_b32_e32 v3, v0
	v_mov_b32_e32 v4, v0
	v_mov_b32_e32 v5, v0
	v_mov_b32_e32 v6, v0
	v_mov_b32_e32 v7, v0
	v_mov_b32_e32 v8, v0
	v_mov_b32_e32 v9, v0
	v_mov_b32_e32 v10, v0
	v_mov_b32_e32 v11, v0
	v_mov_b32_e32 v12, v0
	v_mov_b32_e32 v13, v0
	v_mov_b32_e32 v14, v0
	v_mov_b32_e32 v15, v0
	v_mov_b32_e32 v16, v0
	v_mov_b32_e32 v17, v0
	v_mov_b32_e32 v18, v0
	v_mov_b32_e32 v19, v0
	v_mov_b32_e32 v20, v0
	v_mov_b32_e32 v21, v0
	v_mov_b32_e32 v22, v0
	v_mov_b32_e32 v23, v0
	v_mov_b32_e32 v24, v0
	v_mov_b32_e32 v25, v0
	v_mov_b32_e32 v26, v0
	v_mov_b32_e32 v27, v0
	v_mov_b32_e32 v28, v0
	v_mov_b32_e32 v29, v0
	v_mov_b32_e32 v30, v0
	v_mov_b32_e32 v31, v0
	v_mov_b32_e32 v32, v0
	v_mov_b32_e32 v33, v0
	v_mov_b32_e32 v34, v0
	v_mov_b32_e32 v35, v0
	v_mov_b32_e32 v36, v0
	v_mov_b32_e32 v37, v0
	v_mov_b32_e32 v38, v0
	v_mov_b32_e32 v39, v0
	v_mov_b32_e32 v40, v0
	v_mov_b32_e32 v41, v0
	v_mov_b32_e32 v42, v0
	v_mov_b32_e32 v43, v0
	v_mov_b32_e32 v44, v0
	v_mov_b32_e32 v45, v0
	v_mov_b32_e32 v46, v0
	v_mov_b32_e32 v47, v0
	v_mov_b32_e32 v48, v0
	v_mov_b32_e32 v49, v0
	v_mov_b32_e32 v50, v0
	v_mov_b32_e32 v51, v0
	v_mov_b32_e32 v52, v0
	v_mov_b32_e32 v53, v0
	v_mov_b32_e32 v54, v0
	v_mov_b32_e32 v55, v0
	v_mov_b32_e32 v56, v0
	v_mov_b32_e32 v57, v0
	v_mov_b32_e32 v58, v0
	v_mov_b32_e32 v59, v0
	v_mov_b32_e32 v60, v0
	v_mov_b32_e32 v61, v0
	v_mov_b32_e32 v62, v0
	v_mov_b32_e32 v63, v0
	v_mov_b32_e32 v64, v0
	v_mov_b32_e32 v65, v0
	v_mov_b32_e32 v66, v0
	v_mov_b32_e32 v67, v0
	v_mov_b32_e32 v68, v0
	v_mov_b32_e32 v69, v0
	v_mov_b32_e32 v70, v0
	v_mov_b32_e32 v71, v0
	v_mov_b32_e32 v72, v0
	v_mov_b32_e32 v73, v0
	v_mov_b32_e32 v74, v0
	v_mov_b32_e32 v75, v0
	v_mov_b32_e32 v76, v0
	v_mov_b32_e32 v77, v0
	v_mov_b32_e32 v78, v0
	v_mov_b32_e32 v79, v0
	v_mov_b32_e32 v80, v0
	v_mov_b32_e32 v81, v0
	v_mov_b32_e32 v82, v0
	v_mov_b32_e32 v83, v0
	v_mov_b32_e32 v84, v0
	v_mov_b32_e32 v85, v0
	v_mov_b32_e32 v86, v0
	v_mov_b32_e32 v87, v0
	v_mov_b32_e32 v88, v0
	v_mov_b32_e32 v89, v0
	v_mov_b32_e32 v90, v0
	v_mov_b32_e32 v91, v0
	v_mov_b32_e32 v92, v0
	v_mov_b32_e32 v93, v0
	v_mov_b32_e32 v94, v0
	v_mov_b32_e32 v95, v0
	v_mov_b32_e32 v96, v0
	v_mov_b32_e32 v97, v0
	v_mov_b32_e32 v98, v0
	v_mov_b32_e32 v99, v0
	v_mov_b32_e32 v100, v0
	v_mov_b32_e32 v101, v0
	v_mov_b32_e32 v102, v0
	v_mov_b32_e32 v103, v0
	v_mov_b32_e32 v104, v0
	v_mov_b32_e32 v105, v0
	v_mov_b32_e32 v106, v0
	v_mov_b32_e32 v107, v0
	v_mov_b32_e32 v108, v0
	v_mov_b32_e32 v109, v0
	v_mov_b32_e32 v110, v0
	v_mov_b32_e32 v111, v0
	v_mov_b32_e32 v112, v0
	v_mov_b32_e32 v113, v0
	v_mov_b32_e32 v114, v0
	v_mov_b32_e32 v115, v0
	v_mov_b32_e32 v116, v0
	v_mov_b32_e32 v117, v0
	v_mov_b32_e32 v118, v0
	v_mov_b32_e32 v119, v0
	v_mov_b32_e32 v120, v0
	v_mov_b32_e32 v121, v0
	v_mov_b32_e32 v122, v0
	v_mov_b32_e32 v123, v0
	v_mov_b32_e32 v124, v0
	v_mov_b32_e32 v125, v0
	v_mov_b32_e32 v126, v0
	v_mov_b32_e32 v127, v0
	s_mov_b64 s[12:13], 0x8800100
	s_mov_b64 s[14:15], 0x8880080
	s_mov_b64 s[16:17], 0x8880100
	s_mov_b64 s[18:19], 0x8800180
	s_barrier
